# baseline (speedup 1.0000x reference)
; #define PG8_STAGE(bufoff, gbase, voff) do { _Pragma("unroll") for (int _i = 0; _i < 2; ++_i) \
;         __builtin_amdgcn_global_load_lds((const unsigned*)((const char*)(gbase) + (voff)[_i]), (LAS unsigned*)(lds + (bufoff) + ldsw + _i * 8192), 16, 0, 0); } while (0)
; #define PG8_LDA(dst, b, h) do { _Pragma("unroll") for (int m = 0; m < 4; ++m) _Pragma("unroll") for (int k = 0; k < 2; ++k) dst[m][k] = *(const LAS bf16x8*)(lds + PG8_SA(b, h) + aoff + m * 2048 + k * 1024); } while (0)
; #define PG8_LDB(dst, b, h) do { _Pragma("unroll") for (int n = 0; n < 2; ++n) _Pragma("unroll") for (int k = 0; k < 2; ++k) dst[n][k] = *(const LAS bf16x8*)(lds + PG8_SB(b, h) + boff + n * 2048 + k * 1024); } while (0)
; #define PG8_WAIT_V(n) asm volatile("s_waitcnt vmcnt(" #n ")" ::: "memory")
; #define PG8_WAIT_L(n) asm volatile("s_waitcnt lgkmcnt(" #n ")" ::: "memory")
; #define PG8_BAR __builtin_amdgcn_s_barrier()
; #define PG8_SCHED __builtin_amdgcn_sched_barrier(0)
; template <class Epi, class Sched, bool FUSED = false, bool APERM = false>
; __device__ __forceinline__ void gemm_phase(int wid_s, LAS unsigned char* lds, const Gemm g, const Sched& S, const Epi& E) {
;     ...
;         for (int t = 0; t < nt; t += 2) {
;             const bool last = (t == nt - 2);
;             const char* a1 = cA + (size_t)(t + 1) * kstep;
;             const char* a2 = last ? nA : cA + (size_t)(t + 2) * kstep; const char* b2 = last ? nB : cB + (size_t)(t + 2) * kstep;
;             const char* a3 = a2 + kstep; const char* b3 = b2 + kstep;
;             if (last && has_next) S.a_ready(nxt);
;             PG8_LDB(B0, 0, 0); PG8_LDB(B1, 0, 1); PG8_SCHED; PG8_LDA(At, 0, 0); PG8_STAGE(PG8_SA(1, 1), a1 + hstep, voffA);
;             PG8_WAIT_V(8); PG8_WAIT_L(0); PG8_BAR; PG8_MMA(0, 0, At, B0); PG8_MMA(0, 1, At, B1); PG8_BAR; PG8_SCHED;
;             PG8_LDA(At, 0, 1); PG8_STAGE(PG8_SB(0, 0), b2, voffB); PG8_STAGE(PG8_SB(0, 1), b2 + hstep, voffB); PG8_STAGE(PG8_SA(0, 0), a2, voffA);
;             PG8_WAIT_V(8); PG8_WAIT_L(0); PG8_BAR; PG8_MMA(1, 0, At, B0); PG8_MMA(1, 1, At, B1); PG8_BAR; PG8_SCHED;
.LBB0_145:
	s_add_u32 s42, s40, 0xfff80080
	s_addc_u32 s43, s41, -1
	s_add_i32 s68, 0, 0x10000
	s_cmp_eq_u32 s67, 28
	s_cselect_b32 s45, s3, s43
	s_cselect_b32 s44, s10, s42
	s_cselect_b32 s43, s25, s66
	s_cselect_b32 s42, s27, s35
	s_add_i32 s70, 0, 0x14000
	v_add_u32_e32 v144, s68, v227
	v_add_u32_e32 v160, s70, v227
	ds_read_b128 v[132:135], v144
	ds_read_b128 v[136:139], v144 offset:1024
	ds_read_b128 v[140:143], v144 offset:2048
	ds_read_b128 v[144:147], v144 offset:3072
	ds_read_b128 v[148:151], v160
	ds_read_b128 v[152:155], v160 offset:1024
	ds_read_b128 v[156:159], v160 offset:2048
	ds_read_b128 v[160:163], v160 offset:3072
	v_lshl_add_u64 v[214:215], s[40:41], 0, v[212:213]
	s_add_i32 m0, s52, 0xc000
	ds_read_b128 v[164:167], v228
	ds_read_b128 v[168:171], v228 offset:1024
	ds_read_b128 v[172:175], v228 offset:2048
	ds_read_b128 v[176:179], v228 offset:3072
	ds_read_b128 v[180:183], v228 offset:4096
	ds_read_b128 v[184:187], v228 offset:5120
	ds_read_b128 v[188:191], v228 offset:6144
	ds_read_b128 v[192:195], v228 offset:7168
	global_load_lds_dwordx4 v[214:215], off
	s_add_i32 m0, s52, 0xe000
	v_lshl_add_u64 v[214:215], s[40:41], 0, v[210:211]
	global_load_lds_dwordx4 v[214:215], off
	s_waitcnt vmcnt(8)
	s_waitcnt lgkmcnt(0)
	s_barrier
	v_mfma_f32_16x16x32_f16 v[128:131], v[132:135], v[164:167], v[128:131]
	v_mfma_f32_16x16x32_f16 v[124:127], v[140:143], v[164:167], v[124:127]
	v_mfma_f32_16x16x32_f16 v[112:115], v[132:135], v[172:175], v[112:115]
	v_mfma_f32_16x16x32_f16 v[108:111], v[140:143], v[172:175], v[108:111]
	v_mfma_f32_16x16x32_f16 v[96:99], v[132:135], v[180:183], v[96:99]
	v_mfma_f32_16x16x32_f16 v[92:95], v[140:143], v[180:183], v[92:95]
	v_mfma_f32_16x16x32_f16 v[80:83], v[132:135], v[188:191], v[80:83]
	v_mfma_f32_16x16x32_f16 v[76:79], v[140:143], v[188:191], v[76:79]
	v_mfma_f32_16x16x32_f16 v[128:131], v[136:139], v[168:171], v[128:131]
	v_mfma_f32_16x16x32_f16 v[124:127], v[144:147], v[168:171], v[124:127]
	v_mfma_f32_16x16x32_f16 v[112:115], v[136:139], v[176:179], v[112:115]
	v_mfma_f32_16x16x32_f16 v[108:111], v[144:147], v[176:179], v[108:111]
	v_mfma_f32_16x16x32_f16 v[96:99], v[136:139], v[184:187], v[96:99]
	v_mfma_f32_16x16x32_f16 v[92:95], v[144:147], v[184:187], v[92:95]
	v_mfma_f32_16x16x32_f16 v[80:83], v[136:139], v[192:195], v[80:83]
	v_mfma_f32_16x16x32_f16 v[76:79], v[144:147], v[192:195], v[76:79]
	v_mfma_f32_16x16x32_f16 v[120:123], v[148:151], v[164:167], v[120:123]
	v_mfma_f32_16x16x32_f16 v[116:119], v[156:159], v[164:167], v[116:119]
	v_mfma_f32_16x16x32_f16 v[104:107], v[148:151], v[172:175], v[104:107]
	v_mfma_f32_16x16x32_f16 v[100:103], v[156:159], v[172:175], v[100:103]
	v_mfma_f32_16x16x32_f16 v[88:91], v[148:151], v[180:183], v[88:91]
	v_mfma_f32_16x16x32_f16 v[84:87], v[156:159], v[180:183], v[84:87]
	v_mfma_f32_16x16x32_f16 v[68:71], v[148:151], v[188:191], v[68:71]
	v_mfma_f32_16x16x32_f16 v[72:75], v[156:159], v[188:191], v[72:75]
	v_mfma_f32_16x16x32_f16 v[120:123], v[152:155], v[168:171], v[120:123]
	v_mfma_f32_16x16x32_f16 v[116:119], v[160:163], v[168:171], v[116:119]
	v_mfma_f32_16x16x32_f16 v[104:107], v[152:155], v[176:179], v[104:107]
	v_mfma_f32_16x16x32_f16 v[100:103], v[160:163], v[176:179], v[100:103]
	v_mfma_f32_16x16x32_f16 v[88:91], v[152:155], v[184:187], v[88:91]
	v_mfma_f32_16x16x32_f16 v[84:87], v[160:163], v[184:187], v[84:87]
	v_mfma_f32_16x16x32_f16 v[68:71], v[152:155], v[192:195], v[68:71]
	v_mfma_f32_16x16x32_f16 v[72:75], v[160:163], v[192:195], v[72:75]
	s_barrier
	s_add_i32 s68, s68, s51
	v_lshl_add_u64 v[214:215], s[42:43], 0, v[0:1]
	s_mov_b32 m0, s68
	ds_read_b128 v[164:167], v228 offset:16384
	ds_read_b128 v[168:171], v228 offset:17408
	ds_read_b128 v[172:175], v228 offset:18432
	ds_read_b128 v[176:179], v228 offset:19456
	ds_read_b128 v[180:183], v228 offset:20480
	ds_read_b128 v[184:187], v228 offset:21504
	ds_read_b128 v[188:191], v228 offset:22528
	ds_read_b128 v[192:195], v228 offset:23552
	global_load_lds_dwordx4 v[214:215], off
	s_add_i32 m0, s68, 0x2000
	s_add_u32 s68, s42, 0x80000
	v_lshl_add_u64 v[216:217], s[42:43], 0, v[208:209]
	s_addc_u32 s69, s43, 0
	s_add_i32 s70, s70, s51
	global_load_lds_dwordx4 v[216:217], off
	v_lshl_add_u64 v[218:219], s[68:69], 0, v[0:1]
	s_mov_b32 m0, s70
	v_lshl_add_u64 v[220:221], s[44:45], 0, v[208:209]
	global_load_lds_dwordx4 v[218:219], off
	s_add_i32 m0, s70, 0x2000
	v_lshl_add_u64 v[218:219], s[68:69], 0, v[208:209]
	global_load_lds_dwordx4 v[218:219], off
	s_mov_b32 m0, s52
	v_lshl_add_u64 v[218:219], s[44:45], 0, v[0:1]
	global_load_lds_dwordx4 v[218:219], off
	s_mov_b32 m0, s53
	s_nop 0
	global_load_lds_dwordx4 v[220:221], off
	s_waitcnt vmcnt(8)
	s_waitcnt lgkmcnt(0)
	s_barrier
; #define PG8_STAGE(bufoff, gbase, voff) do { _Pragma("unroll") for (int _i = 0; _i < 2; ++_i) \
;         __builtin_amdgcn_global_load_lds((const unsigned*)((const char*)(gbase) + (voff)[_i]), (LAS unsigned*)(lds + (bufoff) + ldsw + _i * 8192), 16, 0, 0); } while (0)
; #define PG8_LDA(dst, b, h) do { _Pragma("unroll") for (int m = 0; m < 4; ++m) _Pragma("unroll") for (int k = 0; k < 2; ++k) dst[m][k] = *(const LAS bf16x8*)(lds + PG8_SA(b, h) + aoff + m * 2048 + k * 1024); } while (0)
; #define PG8_LDB(dst, b, h) do { _Pragma("unroll") for (int n = 0; n < 2; ++n) _Pragma("unroll") for (int k = 0; k < 2; ++k) dst[n][k] = *(const LAS bf16x8*)(lds + PG8_SB(b, h) + boff + n * 2048 + k * 1024); } while (0)
; #define PG8_WAIT_V(n) asm volatile("s_waitcnt vmcnt(" #n ")" ::: "memory")
; #define PG8_WAIT_L(n) asm volatile("s_waitcnt lgkmcnt(" #n ")" ::: "memory")
; #define PG8_BAR __builtin_amdgcn_s_barrier()
; #define PG8_SCHED __builtin_amdgcn_sched_barrier(0)
; template <class Epi, class Sched, bool FUSED = false, bool APERM = false>
; __device__ __forceinline__ void gemm_phase(int wid_s, LAS unsigned char* lds, const Gemm g, const Sched& S, const Epi& E) {
;     ...
;             PG8_WAIT_V(8); PG8_WAIT_L(0); PG8_BAR; PG8_MMA(1, 0, At, B0); PG8_MMA(1, 1, At, B1); PG8_BAR; PG8_SCHED;
;             PG8_LDB(B0, 1, 0); PG8_LDB(B1, 1, 1); PG8_SCHED; PG8_LDA(At, 1, 0); PG8_STAGE(PG8_SA(0, 1), a2 + hstep, voffA);
;             PG8_WAIT_V(8); PG8_WAIT_L(0); PG8_BAR; PG8_MMA(0, 0, At, B0); PG8_MMA(0, 1, At, B1); PG8_BAR; PG8_SCHED;
	v_mfma_f32_16x16x32_f16 v[64:67], v[132:135], v[164:167], v[64:67]
	v_mfma_f32_16x16x32_f16 v[60:63], v[140:143], v[164:167], v[60:63]
	v_mfma_f32_16x16x32_f16 v[48:51], v[132:135], v[172:175], v[48:51]
	v_mfma_f32_16x16x32_f16 v[44:47], v[140:143], v[172:175], v[44:47]
	v_mfma_f32_16x16x32_f16 v[32:35], v[132:135], v[180:183], v[32:35]
	v_mfma_f32_16x16x32_f16 v[28:31], v[140:143], v[180:183], v[28:31]
	v_mfma_f32_16x16x32_f16 v[12:15], v[132:135], v[188:191], v[12:15]
	v_mfma_f32_16x16x32_f16 v[16:19], v[140:143], v[188:191], v[16:19]
	v_mfma_f32_16x16x32_f16 v[64:67], v[136:139], v[168:171], v[64:67]
	v_mfma_f32_16x16x32_f16 v[60:63], v[144:147], v[168:171], v[60:63]
	v_mfma_f32_16x16x32_f16 v[48:51], v[136:139], v[176:179], v[48:51]
	v_mfma_f32_16x16x32_f16 v[44:47], v[144:147], v[176:179], v[44:47]
	v_mfma_f32_16x16x32_f16 v[32:35], v[136:139], v[184:187], v[32:35]
	v_mfma_f32_16x16x32_f16 v[28:31], v[144:147], v[184:187], v[28:31]
	v_mfma_f32_16x16x32_f16 v[12:15], v[136:139], v[192:195], v[12:15]
	v_mfma_f32_16x16x32_f16 v[16:19], v[144:147], v[192:195], v[16:19]
	v_mfma_f32_16x16x32_f16 v[56:59], v[148:151], v[164:167], v[56:59]
	v_mfma_f32_16x16x32_f16 v[52:55], v[156:159], v[164:167], v[52:55]
	v_mfma_f32_16x16x32_f16 v[40:43], v[148:151], v[172:175], v[40:43]
	v_mfma_f32_16x16x32_f16 v[36:39], v[156:159], v[172:175], v[36:39]
	v_mfma_f32_16x16x32_f16 v[24:27], v[148:151], v[180:183], v[24:27]
	v_mfma_f32_16x16x32_f16 v[20:23], v[156:159], v[180:183], v[20:23]
	v_mfma_f32_16x16x32_f16 v[4:7], v[148:151], v[188:191], v[4:7]
	v_mfma_f32_16x16x32_f16 v[8:11], v[156:159], v[188:191], v[8:11]
	v_mfma_f32_16x16x32_f16 v[56:59], v[152:155], v[168:171], v[56:59]
	v_mfma_f32_16x16x32_f16 v[52:55], v[160:163], v[168:171], v[52:55]
	v_mfma_f32_16x16x32_f16 v[40:43], v[152:155], v[176:179], v[40:43]
	v_mfma_f32_16x16x32_f16 v[36:39], v[160:163], v[176:179], v[36:39]
	v_mfma_f32_16x16x32_f16 v[24:27], v[152:155], v[184:187], v[24:27]
	v_mfma_f32_16x16x32_f16 v[20:23], v[160:163], v[184:187], v[20:23]
	v_mfma_f32_16x16x32_f16 v[4:7], v[152:155], v[192:195], v[4:7]
	v_mfma_f32_16x16x32_f16 v[8:11], v[160:163], v[192:195], v[8:11]
	s_barrier
	s_add_i32 s68, 0, 0x18000
	s_add_i32 s69, 0, 0x1c000
	v_add_u32_e32 v144, s68, v227
	v_add_u32_e32 v160, s69, v227
	ds_read_b128 v[132:135], v144
	ds_read_b128 v[136:139], v144 offset:1024
	ds_read_b128 v[140:143], v144 offset:2048
	ds_read_b128 v[144:147], v144 offset:3072
	ds_read_b128 v[148:151], v160
	ds_read_b128 v[152:155], v160 offset:1024
	ds_read_b128 v[156:159], v160 offset:2048
	ds_read_b128 v[160:163], v160 offset:3072
	s_add_u32 s44, s44, 0x80000
	s_addc_u32 s45, s45, 0
	s_mov_b32 m0, s54
	v_lshl_add_u64 v[222:223], s[44:45], 0, v[0:1]
	ds_read_b128 v[164:167], v228 offset:32768
	ds_read_b128 v[168:171], v228 offset:33792
	ds_read_b128 v[172:175], v228 offset:34816
	ds_read_b128 v[176:179], v228 offset:35840
	ds_read_b128 v[180:183], v228 offset:36864
	ds_read_b128 v[184:187], v228 offset:37888
	ds_read_b128 v[188:191], v228 offset:38912
	ds_read_b128 v[192:195], v228 offset:39936
	global_load_lds_dwordx4 v[222:223], off
	s_mov_b32 m0, s55
	v_lshl_add_u64 v[222:223], s[44:45], 0, v[208:209]
	global_load_lds_dwordx4 v[222:223], off
	s_waitcnt vmcnt(8)
	s_waitcnt lgkmcnt(0)
	s_barrier
	v_mfma_f32_16x16x32_f16 v[128:131], v[132:135], v[164:167], v[128:131]
	v_mfma_f32_16x16x32_f16 v[124:127], v[140:143], v[164:167], v[124:127]
	v_mfma_f32_16x16x32_f16 v[112:115], v[132:135], v[172:175], v[112:115]
	v_mfma_f32_16x16x32_f16 v[108:111], v[140:143], v[172:175], v[108:111]
	v_mfma_f32_16x16x32_f16 v[96:99], v[132:135], v[180:183], v[96:99]
	v_mfma_f32_16x16x32_f16 v[92:95], v[140:143], v[180:183], v[92:95]
	v_mfma_f32_16x16x32_f16 v[80:83], v[132:135], v[188:191], v[80:83]
	v_mfma_f32_16x16x32_f16 v[76:79], v[140:143], v[188:191], v[76:79]
	v_mfma_f32_16x16x32_f16 v[128:131], v[136:139], v[168:171], v[128:131]
	v_mfma_f32_16x16x32_f16 v[124:127], v[144:147], v[168:171], v[124:127]
	v_mfma_f32_16x16x32_f16 v[112:115], v[136:139], v[176:179], v[112:115]
	v_mfma_f32_16x16x32_f16 v[108:111], v[144:147], v[176:179], v[108:111]
	v_mfma_f32_16x16x32_f16 v[96:99], v[136:139], v[184:187], v[96:99]
	v_mfma_f32_16x16x32_f16 v[92:95], v[144:147], v[184:187], v[92:95]
	v_mfma_f32_16x16x32_f16 v[80:83], v[136:139], v[192:195], v[80:83]
	v_mfma_f32_16x16x32_f16 v[76:79], v[144:147], v[192:195], v[76:79]
	v_mfma_f32_16x16x32_f16 v[120:123], v[148:151], v[164:167], v[120:123]
	v_mfma_f32_16x16x32_f16 v[116:119], v[156:159], v[164:167], v[116:119]
	v_mfma_f32_16x16x32_f16 v[104:107], v[148:151], v[172:175], v[104:107]
	v_mfma_f32_16x16x32_f16 v[100:103], v[156:159], v[172:175], v[100:103]
	v_mfma_f32_16x16x32_f16 v[88:91], v[148:151], v[180:183], v[88:91]
	v_mfma_f32_16x16x32_f16 v[84:87], v[156:159], v[180:183], v[84:87]
	v_mfma_f32_16x16x32_f16 v[68:71], v[148:151], v[188:191], v[68:71]
	v_mfma_f32_16x16x32_f16 v[72:75], v[156:159], v[188:191], v[72:75]
	v_mfma_f32_16x16x32_f16 v[120:123], v[152:155], v[168:171], v[120:123]
	v_mfma_f32_16x16x32_f16 v[116:119], v[160:163], v[168:171], v[116:119]
	v_mfma_f32_16x16x32_f16 v[104:107], v[152:155], v[176:179], v[104:107]
	v_mfma_f32_16x16x32_f16 v[100:103], v[160:163], v[176:179], v[100:103]
	v_mfma_f32_16x16x32_f16 v[88:91], v[152:155], v[184:187], v[88:91]
	v_mfma_f32_16x16x32_f16 v[84:87], v[160:163], v[184:187], v[84:87]
	v_mfma_f32_16x16x32_f16 v[68:71], v[152:155], v[192:195], v[68:71]
	v_mfma_f32_16x16x32_f16 v[72:75], v[160:163], v[192:195], v[72:75]
	s_barrier
; #define PG8_STAGE(bufoff, gbase, voff) do { _Pragma("unroll") for (int _i = 0; _i < 2; ++_i) \
;         __builtin_amdgcn_global_load_lds((const unsigned*)((const char*)(gbase) + (voff)[_i]), (LAS unsigned*)(lds + (bufoff) + ldsw + _i * 8192), 16, 0, 0); } while (0)
; #define PG8_LDA(dst, b, h) do { _Pragma("unroll") for (int m = 0; m < 4; ++m) _Pragma("unroll") for (int k = 0; k < 2; ++k) dst[m][k] = *(const LAS bf16x8*)(lds + PG8_SA(b, h) + aoff + m * 2048 + k * 1024); } while (0)
; #define PG8_WAIT_V(n) asm volatile("s_waitcnt vmcnt(" #n ")" ::: "memory")
; #define PG8_WAIT_L(n) asm volatile("s_waitcnt lgkmcnt(" #n ")" ::: "memory")
; #define PG8_BAR __builtin_amdgcn_s_barrier()
; #define PG8_SCHED __builtin_amdgcn_sched_barrier(0)
; template <class Epi, class Sched, bool FUSED = false, bool APERM = false>
; __device__ __forceinline__ void gemm_phase(int wid_s, LAS unsigned char* lds, const Gemm g, const Sched& S, const Epi& E) {
;     ...
;             PG8_WAIT_V(8); PG8_WAIT_L(0); PG8_BAR; PG8_MMA(0, 0, At, B0); PG8_MMA(0, 1, At, B1); PG8_BAR; PG8_SCHED;
;             PG8_LDA(At, 1, 1); PG8_STAGE(PG8_SB(1, 0), b3, voffB); PG8_STAGE(PG8_SB(1, 1), b3 + hstep, voffB); PG8_STAGE(PG8_SA(1, 0), a3, voffA);
;             PG8_WAIT_V(8); PG8_WAIT_L(0); PG8_BAR; PG8_MMA(1, 0, At, B0); PG8_MMA(1, 1, At, B1); PG8_BAR; PG8_SCHED;
;         }
;         if (wr == 0) PG8_BAR;
	s_add_i32 s44, s68, s51
	v_lshl_add_u64 v[214:215], v[214:215], 0, s[12:13]
	s_mov_b32 m0, s44
	ds_read_b128 v[164:167], v228 offset:49152
	ds_read_b128 v[168:171], v228 offset:50176
	ds_read_b128 v[172:175], v228 offset:51200
	ds_read_b128 v[176:179], v228 offset:52224
	ds_read_b128 v[180:183], v228 offset:53248
	ds_read_b128 v[184:187], v228 offset:54272
	ds_read_b128 v[188:191], v228 offset:55296
	ds_read_b128 v[192:195], v228 offset:56320
	global_load_lds_dwordx4 v[214:215], off
	s_add_i32 m0, s44, 0x2000
	s_add_u32 s42, s42, 0x80080
	v_lshl_add_u64 v[214:215], v[216:217], 0, s[12:13]
	s_addc_u32 s43, s43, 0
	s_add_i32 s44, s69, s51
	global_load_lds_dwordx4 v[214:215], off
	s_mov_b32 m0, s44
	v_lshl_add_u64 v[214:215], s[42:43], 0, v[0:1]
	global_load_lds_dwordx4 v[214:215], off
	s_add_i32 m0, s44, 0x2000
	v_lshl_add_u64 v[214:215], s[42:43], 0, v[208:209]
	global_load_lds_dwordx4 v[214:215], off
	s_mov_b32 m0, s59
	v_lshl_add_u64 v[214:215], v[218:219], 0, s[12:13]
	global_load_lds_dwordx4 v[214:215], off
	s_mov_b32 m0, s60
	v_lshl_add_u64 v[214:215], v[220:221], 0, s[12:13]
	global_load_lds_dwordx4 v[214:215], off
	s_waitcnt vmcnt(8)
	s_waitcnt lgkmcnt(0)
	s_barrier
	v_mfma_f32_16x16x32_f16 v[64:67], v[132:135], v[164:167], v[64:67]
	v_mfma_f32_16x16x32_f16 v[60:63], v[140:143], v[164:167], v[60:63]
	v_mfma_f32_16x16x32_f16 v[48:51], v[132:135], v[172:175], v[48:51]
	v_mfma_f32_16x16x32_f16 v[44:47], v[140:143], v[172:175], v[44:47]
	v_mfma_f32_16x16x32_f16 v[32:35], v[132:135], v[180:183], v[32:35]
	v_mfma_f32_16x16x32_f16 v[28:31], v[140:143], v[180:183], v[28:31]
	v_mfma_f32_16x16x32_f16 v[12:15], v[132:135], v[188:191], v[12:15]
	v_mfma_f32_16x16x32_f16 v[16:19], v[140:143], v[188:191], v[16:19]
	v_mfma_f32_16x16x32_f16 v[64:67], v[136:139], v[168:171], v[64:67]
	v_mfma_f32_16x16x32_f16 v[60:63], v[144:147], v[168:171], v[60:63]
	v_mfma_f32_16x16x32_f16 v[48:51], v[136:139], v[176:179], v[48:51]
	v_mfma_f32_16x16x32_f16 v[44:47], v[144:147], v[176:179], v[44:47]
	v_mfma_f32_16x16x32_f16 v[32:35], v[136:139], v[184:187], v[32:35]
	v_mfma_f32_16x16x32_f16 v[28:31], v[144:147], v[184:187], v[28:31]
	v_mfma_f32_16x16x32_f16 v[12:15], v[136:139], v[192:195], v[12:15]
	v_mfma_f32_16x16x32_f16 v[16:19], v[144:147], v[192:195], v[16:19]
	v_mfma_f32_16x16x32_f16 v[56:59], v[148:151], v[164:167], v[56:59]
	v_mfma_f32_16x16x32_f16 v[52:55], v[156:159], v[164:167], v[52:55]
	v_mfma_f32_16x16x32_f16 v[40:43], v[148:151], v[172:175], v[40:43]
	v_mfma_f32_16x16x32_f16 v[36:39], v[156:159], v[172:175], v[36:39]
	v_mfma_f32_16x16x32_f16 v[24:27], v[148:151], v[180:183], v[24:27]
	v_mfma_f32_16x16x32_f16 v[20:23], v[156:159], v[180:183], v[20:23]
	v_mfma_f32_16x16x32_f16 v[4:7], v[148:151], v[188:191], v[4:7]
	v_mfma_f32_16x16x32_f16 v[8:11], v[156:159], v[188:191], v[8:11]
	v_mfma_f32_16x16x32_f16 v[56:59], v[152:155], v[168:171], v[56:59]
	v_mfma_f32_16x16x32_f16 v[52:55], v[160:163], v[168:171], v[52:55]
	v_mfma_f32_16x16x32_f16 v[40:43], v[152:155], v[176:179], v[40:43]
	v_mfma_f32_16x16x32_f16 v[36:39], v[160:163], v[176:179], v[36:39]
	v_mfma_f32_16x16x32_f16 v[24:27], v[152:155], v[184:187], v[24:27]
	v_mfma_f32_16x16x32_f16 v[20:23], v[160:163], v[184:187], v[20:23]
	v_mfma_f32_16x16x32_f16 v[4:7], v[152:155], v[192:195], v[4:7]
	v_mfma_f32_16x16x32_f16 v[8:11], v[160:163], v[192:195], v[8:11]
	s_barrier
	s_add_i32 s67, s67, 2
	s_add_u32 s35, s35, 0x100
	s_addc_u32 s66, s66, 0
	s_add_u32 s40, s40, 0x100
	s_addc_u32 s41, s41, 0
	s_cmp_gt_u32 s67, 29
	s_cbranch_scc0 .LBB0_145
	s_and_b64 vcc, exec, s[16:17]
	s_cbranch_vccz .LBB0_148
	s_barrier

; #define PG8_STAGE(bufoff, gbase, voff) do { _Pragma("unroll") for (int _i = 0; _i < 2; ++_i) \
;         __builtin_amdgcn_global_load_lds((const unsigned*)((const char*)(gbase) + (voff)[_i]), (LAS unsigned*)(lds + (bufoff) + ldsw + _i * 8192), 16, 0, 0); } while (0)
; #define PG8_LDA(dst, b, h) do { _Pragma("unroll") for (int m = 0; m < 4; ++m) _Pragma("unroll") for (int k = 0; k < 2; ++k) dst[m][k] = *(const LAS bf16x8*)(lds + PG8_SA(b, h) + aoff + m * 2048 + k * 1024); } while (0)
; #define PG8_LDB(dst, b, h) do { _Pragma("unroll") for (int n = 0; n < 2; ++n) _Pragma("unroll") for (int k = 0; k < 2; ++k) dst[n][k] = *(const LAS bf16x8*)(lds + PG8_SB(b, h) + boff + n * 2048 + k * 1024); } while (0)
; #define PG8_WAIT_V(n) asm volatile("s_waitcnt vmcnt(" #n ")" ::: "memory")
; #define PG8_WAIT_L(n) asm volatile("s_waitcnt lgkmcnt(" #n ")" ::: "memory")
; #define PG8_BAR __builtin_amdgcn_s_barrier()
; #define PG8_SCHED __builtin_amdgcn_sched_barrier(0)
; template <class Epi, class Sched, bool FUSED = false, bool APERM = false>
; __device__ __forceinline__ void gemm_phase(int wid_s, LAS unsigned char* lds, const Gemm g, const Sched& S, const Epi& E) {
;     ...
;         for (int t = 0; t < nt; t += 2) {
;             const bool last = (t == nt - 2);
;             const char* a1 = cA + (size_t)(t + 1) * kstep;
;             const char* a2 = last ? nA : cA + (size_t)(t + 2) * kstep; const char* b2 = last ? nB : cB + (size_t)(t + 2) * kstep;
;             const char* a3 = a2 + kstep; const char* b3 = b2 + kstep;
;             if (last && has_next) S.a_ready(nxt);
;             PG8_LDB(B0, 0, 0); PG8_LDB(B1, 0, 1); PG8_SCHED; PG8_LDA(At, 0, 0); PG8_STAGE(PG8_SA(1, 1), a1 + hstep, voffA);
;             PG8_WAIT_V(8); PG8_WAIT_L(0); PG8_BAR; PG8_MMA(0, 0, At, B0); PG8_MMA(0, 1, At, B1); PG8_BAR; PG8_SCHED;
;             PG8_LDA(At, 0, 1); PG8_STAGE(PG8_SB(0, 0), b2, voffB); PG8_STAGE(PG8_SB(0, 1), b2 + hstep, voffB); PG8_STAGE(PG8_SA(0, 0), a2, voffA);
;             PG8_WAIT_V(8); PG8_WAIT_L(0); PG8_BAR; PG8_MMA(1, 0, At, B0); PG8_MMA(1, 1, At, B1); PG8_BAR; PG8_SCHED;
.LBB0_653:
	s_add_u32 s38, s28, s36
	s_addc_u32 s39, s29, s37
	s_add_u32 s38, s38, 0x100
	s_addc_u32 s39, s39, 0
	s_add_u32 s63, s58, s36
	s_addc_u32 s64, s59, s37
	s_add_i32 s65, 0, 0x10000
	s_cmpk_eq_i32 s36, 0xf00
	s_cselect_b32 s41, s27, s39
	s_cselect_b32 s40, s60, s38
	v_add_u32_e32 v143, s65, v3
	s_cselect_b32 s39, s25, s64
	s_cselect_b32 s38, s61, s63
	s_add_i32 s63, 0, 0x14000
	ds_read_b128 v[144:147], v143
	ds_read_b128 v[148:151], v143 offset:1024
	ds_read_b128 v[152:155], v143 offset:2048
	ds_read_b128 v[156:159], v143 offset:3072
	v_add_u32_e32 v143, s63, v3
	ds_read_b128 v[160:163], v143
	ds_read_b128 v[164:167], v143 offset:1024
	ds_read_b128 v[168:171], v143 offset:2048
	ds_read_b128 v[172:175], v143 offset:3072
	v_lshl_add_u64 v[222:223], v[140:141], 0, s[36:37]
	s_add_i32 m0, s15, 0xc000
	ds_read_b128 v[176:179], v142
	ds_read_b128 v[180:183], v142 offset:1024
	ds_read_b128 v[184:187], v142 offset:2048
	ds_read_b128 v[188:191], v142 offset:3072
	ds_read_b128 v[192:195], v142 offset:4096
	ds_read_b128 v[208:211], v142 offset:5120
	ds_read_b128 v[212:215], v142 offset:6144
	ds_read_b128 v[216:219], v142 offset:7168
	global_load_lds_dwordx4 v[222:223], off
	s_add_i32 m0, s15, 0xe000
	v_lshl_add_u64 v[222:223], v[138:139], 0, s[36:37]
	global_load_lds_dwordx4 v[222:223], off
	s_waitcnt vmcnt(8)
	s_waitcnt lgkmcnt(0)
	s_barrier
	v_mfma_f32_16x16x32_f16 v[128:131], v[144:147], v[176:179], v[128:131]
	v_mfma_f32_16x16x32_f16 v[124:127], v[152:155], v[176:179], v[124:127]
	v_mfma_f32_16x16x32_f16 v[112:115], v[144:147], v[184:187], v[112:115]
	v_mfma_f32_16x16x32_f16 v[108:111], v[152:155], v[184:187], v[108:111]
	v_mfma_f32_16x16x32_f16 v[96:99], v[144:147], v[192:195], v[96:99]
	v_mfma_f32_16x16x32_f16 v[92:95], v[152:155], v[192:195], v[92:95]
	v_mfma_f32_16x16x32_f16 v[80:83], v[144:147], v[212:215], v[80:83]
	v_mfma_f32_16x16x32_f16 v[76:79], v[152:155], v[212:215], v[76:79]
	v_mfma_f32_16x16x32_f16 v[128:131], v[148:151], v[180:183], v[128:131]
	v_mfma_f32_16x16x32_f16 v[124:127], v[156:159], v[180:183], v[124:127]
	v_mfma_f32_16x16x32_f16 v[112:115], v[148:151], v[188:191], v[112:115]
	v_mfma_f32_16x16x32_f16 v[108:111], v[156:159], v[188:191], v[108:111]
	v_mfma_f32_16x16x32_f16 v[96:99], v[148:151], v[208:211], v[96:99]
	v_mfma_f32_16x16x32_f16 v[92:95], v[156:159], v[208:211], v[92:95]
	v_mfma_f32_16x16x32_f16 v[80:83], v[148:151], v[216:219], v[80:83]
	v_mfma_f32_16x16x32_f16 v[76:79], v[156:159], v[216:219], v[76:79]
	v_mfma_f32_16x16x32_f16 v[120:123], v[160:163], v[176:179], v[120:123]
	v_mfma_f32_16x16x32_f16 v[116:119], v[168:171], v[176:179], v[116:119]
	v_mfma_f32_16x16x32_f16 v[104:107], v[160:163], v[184:187], v[104:107]
	v_mfma_f32_16x16x32_f16 v[100:103], v[168:171], v[184:187], v[100:103]
	v_mfma_f32_16x16x32_f16 v[88:91], v[160:163], v[192:195], v[88:91]
	v_mfma_f32_16x16x32_f16 v[84:87], v[168:171], v[192:195], v[84:87]
	v_mfma_f32_16x16x32_f16 v[72:75], v[160:163], v[212:215], v[72:75]
	v_mfma_f32_16x16x32_f16 v[68:71], v[168:171], v[212:215], v[68:71]
	v_mfma_f32_16x16x32_f16 v[120:123], v[164:167], v[180:183], v[120:123]
	v_mfma_f32_16x16x32_f16 v[116:119], v[172:175], v[180:183], v[116:119]
	v_mfma_f32_16x16x32_f16 v[104:107], v[164:167], v[188:191], v[104:107]
	v_mfma_f32_16x16x32_f16 v[100:103], v[172:175], v[188:191], v[100:103]
	v_mfma_f32_16x16x32_f16 v[88:91], v[164:167], v[208:211], v[88:91]
	v_mfma_f32_16x16x32_f16 v[84:87], v[172:175], v[208:211], v[84:87]
	v_mfma_f32_16x16x32_f16 v[72:75], v[164:167], v[216:219], v[72:75]
	v_mfma_f32_16x16x32_f16 v[68:71], v[172:175], v[216:219], v[68:71]
	s_barrier
	s_add_i32 s64, s65, s49
	v_lshl_add_u64 v[222:223], s[38:39], 0, v[0:1]
	s_mov_b32 m0, s64
	ds_read_b128 v[176:179], v142 offset:16384
	ds_read_b128 v[180:183], v142 offset:17408
	ds_read_b128 v[184:187], v142 offset:18432
	ds_read_b128 v[188:191], v142 offset:19456
	ds_read_b128 v[192:195], v142 offset:20480
	ds_read_b128 v[208:211], v142 offset:21504
	ds_read_b128 v[212:215], v142 offset:22528
	ds_read_b128 v[216:219], v142 offset:23552
	global_load_lds_dwordx4 v[222:223], off
	s_add_i32 m0, s64, 0x2000
	s_add_u32 s64, s38, 0x80000
	v_lshl_add_u64 v[224:225], s[38:39], 0, v[132:133]
	s_addc_u32 s65, s39, 0
	s_add_i32 s63, s63, s49
	global_load_lds_dwordx4 v[224:225], off
	v_lshl_add_u64 v[226:227], s[64:65], 0, v[0:1]
	s_mov_b32 m0, s63
	v_lshl_add_u64 v[228:229], s[40:41], 0, v[132:133]
	global_load_lds_dwordx4 v[226:227], off
	s_add_i32 m0, s63, 0x2000
	v_lshl_add_u64 v[226:227], s[64:65], 0, v[132:133]
	global_load_lds_dwordx4 v[226:227], off
	s_mov_b32 m0, s15
	v_lshl_add_u64 v[226:227], s[40:41], 0, v[0:1]
	global_load_lds_dwordx4 v[226:227], off
	s_mov_b32 m0, s50
	s_nop 0
	global_load_lds_dwordx4 v[228:229], off
	s_waitcnt vmcnt(8)
	s_waitcnt lgkmcnt(0)
	s_barrier
; #define PG8_STAGE(bufoff, gbase, voff) do { _Pragma("unroll") for (int _i = 0; _i < 2; ++_i) \
;         __builtin_amdgcn_global_load_lds((const unsigned*)((const char*)(gbase) + (voff)[_i]), (LAS unsigned*)(lds + (bufoff) + ldsw + _i * 8192), 16, 0, 0); } while (0)
; #define PG8_LDA(dst, b, h) do { _Pragma("unroll") for (int m = 0; m < 4; ++m) _Pragma("unroll") for (int k = 0; k < 2; ++k) dst[m][k] = *(const LAS bf16x8*)(lds + PG8_SA(b, h) + aoff + m * 2048 + k * 1024); } while (0)
; #define PG8_LDB(dst, b, h) do { _Pragma("unroll") for (int n = 0; n < 2; ++n) _Pragma("unroll") for (int k = 0; k < 2; ++k) dst[n][k] = *(const LAS bf16x8*)(lds + PG8_SB(b, h) + boff + n * 2048 + k * 1024); } while (0)
; #define PG8_WAIT_V(n) asm volatile("s_waitcnt vmcnt(" #n ")" ::: "memory")
; #define PG8_WAIT_L(n) asm volatile("s_waitcnt lgkmcnt(" #n ")" ::: "memory")
; #define PG8_BAR __builtin_amdgcn_s_barrier()
; #define PG8_SCHED __builtin_amdgcn_sched_barrier(0)
; template <class Epi, class Sched, bool FUSED = false, bool APERM = false>
; __device__ __forceinline__ void gemm_phase(int wid_s, LAS unsigned char* lds, const Gemm g, const Sched& S, const Epi& E) {
;     ...
;             PG8_WAIT_V(8); PG8_WAIT_L(0); PG8_BAR; PG8_MMA(1, 0, At, B0); PG8_MMA(1, 1, At, B1); PG8_BAR; PG8_SCHED;
;             PG8_LDB(B0, 1, 0); PG8_LDB(B1, 1, 1); PG8_SCHED; PG8_LDA(At, 1, 0); PG8_STAGE(PG8_SA(0, 1), a2 + hstep, voffA);
;             PG8_WAIT_V(8); PG8_WAIT_L(0); PG8_BAR; PG8_MMA(0, 0, At, B0); PG8_MMA(0, 1, At, B1); PG8_BAR; PG8_SCHED;
	v_mfma_f32_16x16x32_f16 v[64:67], v[144:147], v[176:179], v[64:67]
	v_mfma_f32_16x16x32_f16 v[60:63], v[152:155], v[176:179], v[60:63]
	v_mfma_f32_16x16x32_f16 v[48:51], v[144:147], v[184:187], v[48:51]
	v_mfma_f32_16x16x32_f16 v[44:47], v[152:155], v[184:187], v[44:47]
	v_mfma_f32_16x16x32_f16 v[32:35], v[144:147], v[192:195], v[32:35]
	v_mfma_f32_16x16x32_f16 v[28:31], v[152:155], v[192:195], v[28:31]
	v_mfma_f32_16x16x32_f16 v[16:19], v[144:147], v[212:215], v[16:19]
	v_mfma_f32_16x16x32_f16 v[12:15], v[152:155], v[212:215], v[12:15]
	v_mfma_f32_16x16x32_f16 v[64:67], v[148:151], v[180:183], v[64:67]
	v_mfma_f32_16x16x32_f16 v[60:63], v[156:159], v[180:183], v[60:63]
	v_mfma_f32_16x16x32_f16 v[48:51], v[148:151], v[188:191], v[48:51]
	v_mfma_f32_16x16x32_f16 v[44:47], v[156:159], v[188:191], v[44:47]
	v_mfma_f32_16x16x32_f16 v[32:35], v[148:151], v[208:211], v[32:35]
	v_mfma_f32_16x16x32_f16 v[28:31], v[156:159], v[208:211], v[28:31]
	v_mfma_f32_16x16x32_f16 v[16:19], v[148:151], v[216:219], v[16:19]
	v_mfma_f32_16x16x32_f16 v[12:15], v[156:159], v[216:219], v[12:15]
	v_mfma_f32_16x16x32_f16 v[56:59], v[160:163], v[176:179], v[56:59]
	v_mfma_f32_16x16x32_f16 v[52:55], v[168:171], v[176:179], v[52:55]
	v_mfma_f32_16x16x32_f16 v[40:43], v[160:163], v[184:187], v[40:43]
	v_mfma_f32_16x16x32_f16 v[36:39], v[168:171], v[184:187], v[36:39]
	v_mfma_f32_16x16x32_f16 v[24:27], v[160:163], v[192:195], v[24:27]
	v_mfma_f32_16x16x32_f16 v[20:23], v[168:171], v[192:195], v[20:23]
	v_mfma_f32_16x16x32_f16 v[8:11], v[160:163], v[212:215], v[8:11]
	v_mfma_f32_16x16x32_f16 v[4:7], v[168:171], v[212:215], v[4:7]
	v_mfma_f32_16x16x32_f16 v[56:59], v[164:167], v[180:183], v[56:59]
	v_mfma_f32_16x16x32_f16 v[52:55], v[172:175], v[180:183], v[52:55]
	v_mfma_f32_16x16x32_f16 v[40:43], v[164:167], v[188:191], v[40:43]
	v_mfma_f32_16x16x32_f16 v[36:39], v[172:175], v[188:191], v[36:39]
	v_mfma_f32_16x16x32_f16 v[24:27], v[164:167], v[208:211], v[24:27]
	v_mfma_f32_16x16x32_f16 v[20:23], v[172:175], v[208:211], v[20:23]
	v_mfma_f32_16x16x32_f16 v[8:11], v[164:167], v[216:219], v[8:11]
	v_mfma_f32_16x16x32_f16 v[4:7], v[172:175], v[216:219], v[4:7]
	s_barrier
	s_add_i32 s63, 0, 0x18000
	v_add_u32_e32 v143, s63, v3
	s_add_i32 s64, 0, 0x1c000
	ds_read_b128 v[144:147], v143
	ds_read_b128 v[148:151], v143 offset:1024
	ds_read_b128 v[152:155], v143 offset:2048
	ds_read_b128 v[156:159], v143 offset:3072
	v_add_u32_e32 v143, s64, v3
	ds_read_b128 v[160:163], v143
	ds_read_b128 v[164:167], v143 offset:1024
	ds_read_b128 v[168:171], v143 offset:2048
	ds_read_b128 v[172:175], v143 offset:3072
	s_add_u32 s40, s40, 0x80000
	s_addc_u32 s41, s41, 0
	s_mov_b32 m0, s51
	v_lshl_add_u64 v[230:231], s[40:41], 0, v[0:1]
	ds_read_b128 v[176:179], v142 offset:32768
	ds_read_b128 v[180:183], v142 offset:33792
	ds_read_b128 v[184:187], v142 offset:34816
	ds_read_b128 v[188:191], v142 offset:35840
	ds_read_b128 v[192:195], v142 offset:36864
	ds_read_b128 v[208:211], v142 offset:37888
	ds_read_b128 v[212:215], v142 offset:38912
	ds_read_b128 v[216:219], v142 offset:39936
	global_load_lds_dwordx4 v[230:231], off
	s_mov_b32 m0, s52
	v_lshl_add_u64 v[230:231], s[40:41], 0, v[132:133]
	global_load_lds_dwordx4 v[230:231], off
	s_waitcnt vmcnt(8)
	s_waitcnt lgkmcnt(0)
	s_barrier
	v_mfma_f32_16x16x32_f16 v[128:131], v[144:147], v[176:179], v[128:131]
	v_mfma_f32_16x16x32_f16 v[124:127], v[152:155], v[176:179], v[124:127]
	v_mfma_f32_16x16x32_f16 v[112:115], v[144:147], v[184:187], v[112:115]
	v_mfma_f32_16x16x32_f16 v[108:111], v[152:155], v[184:187], v[108:111]
	v_mfma_f32_16x16x32_f16 v[96:99], v[144:147], v[192:195], v[96:99]
	v_mfma_f32_16x16x32_f16 v[92:95], v[152:155], v[192:195], v[92:95]
	v_mfma_f32_16x16x32_f16 v[80:83], v[144:147], v[212:215], v[80:83]
	v_mfma_f32_16x16x32_f16 v[76:79], v[152:155], v[212:215], v[76:79]
	v_mfma_f32_16x16x32_f16 v[128:131], v[148:151], v[180:183], v[128:131]
	v_mfma_f32_16x16x32_f16 v[124:127], v[156:159], v[180:183], v[124:127]
	v_mfma_f32_16x16x32_f16 v[112:115], v[148:151], v[188:191], v[112:115]
	v_mfma_f32_16x16x32_f16 v[108:111], v[156:159], v[188:191], v[108:111]
	v_mfma_f32_16x16x32_f16 v[96:99], v[148:151], v[208:211], v[96:99]
	v_mfma_f32_16x16x32_f16 v[92:95], v[156:159], v[208:211], v[92:95]
	v_mfma_f32_16x16x32_f16 v[80:83], v[148:151], v[216:219], v[80:83]
	v_mfma_f32_16x16x32_f16 v[76:79], v[156:159], v[216:219], v[76:79]
	v_mfma_f32_16x16x32_f16 v[120:123], v[160:163], v[176:179], v[120:123]
	v_mfma_f32_16x16x32_f16 v[116:119], v[168:171], v[176:179], v[116:119]
	v_mfma_f32_16x16x32_f16 v[104:107], v[160:163], v[184:187], v[104:107]
	v_mfma_f32_16x16x32_f16 v[100:103], v[168:171], v[184:187], v[100:103]
	v_mfma_f32_16x16x32_f16 v[88:91], v[160:163], v[192:195], v[88:91]
	v_mfma_f32_16x16x32_f16 v[84:87], v[168:171], v[192:195], v[84:87]
	v_mfma_f32_16x16x32_f16 v[72:75], v[160:163], v[212:215], v[72:75]
	v_mfma_f32_16x16x32_f16 v[68:71], v[168:171], v[212:215], v[68:71]
	v_mfma_f32_16x16x32_f16 v[120:123], v[164:167], v[180:183], v[120:123]
	v_mfma_f32_16x16x32_f16 v[116:119], v[172:175], v[180:183], v[116:119]
	v_mfma_f32_16x16x32_f16 v[104:107], v[164:167], v[188:191], v[104:107]
	v_mfma_f32_16x16x32_f16 v[100:103], v[172:175], v[188:191], v[100:103]
	v_mfma_f32_16x16x32_f16 v[88:91], v[164:167], v[208:211], v[88:91]
	v_mfma_f32_16x16x32_f16 v[84:87], v[172:175], v[208:211], v[84:87]
	v_mfma_f32_16x16x32_f16 v[72:75], v[164:167], v[216:219], v[72:75]
	v_mfma_f32_16x16x32_f16 v[68:71], v[172:175], v[216:219], v[68:71]
	s_barrier
; #define PG8_STAGE(bufoff, gbase, voff) do { _Pragma("unroll") for (int _i = 0; _i < 2; ++_i) \
;         __builtin_amdgcn_global_load_lds((const unsigned*)((const char*)(gbase) + (voff)[_i]), (LAS unsigned*)(lds + (bufoff) + ldsw + _i * 8192), 16, 0, 0); } while (0)
; #define PG8_LDA(dst, b, h) do { _Pragma("unroll") for (int m = 0; m < 4; ++m) _Pragma("unroll") for (int k = 0; k < 2; ++k) dst[m][k] = *(const LAS bf16x8*)(lds + PG8_SA(b, h) + aoff + m * 2048 + k * 1024); } while (0)
; #define PG8_WAIT_V(n) asm volatile("s_waitcnt vmcnt(" #n ")" ::: "memory")
; #define PG8_WAIT_L(n) asm volatile("s_waitcnt lgkmcnt(" #n ")" ::: "memory")
; #define PG8_BAR __builtin_amdgcn_s_barrier()
; #define PG8_SCHED __builtin_amdgcn_sched_barrier(0)
; template <class Epi, class Sched, bool FUSED = false, bool APERM = false>
; __device__ __forceinline__ void gemm_phase(int wid_s, LAS unsigned char* lds, const Gemm g, const Sched& S, const Epi& E) {
;     ...
;             PG8_WAIT_V(8); PG8_WAIT_L(0); PG8_BAR; PG8_MMA(0, 0, At, B0); PG8_MMA(0, 1, At, B1); PG8_BAR; PG8_SCHED;
;             PG8_LDA(At, 1, 1); PG8_STAGE(PG8_SB(1, 0), b3, voffB); PG8_STAGE(PG8_SB(1, 1), b3 + hstep, voffB); PG8_STAGE(PG8_SA(1, 0), a3, voffA);
;             PG8_WAIT_V(8); PG8_WAIT_L(0); PG8_BAR; PG8_MMA(1, 0, At, B0); PG8_MMA(1, 1, At, B1); PG8_BAR; PG8_SCHED;
;         }
;         if (wr == 0) PG8_BAR;
	s_add_i32 s40, s63, s49
	v_lshl_add_u64 v[222:223], v[222:223], 0, s[12:13]
	s_mov_b32 m0, s40
	ds_read_b128 v[176:179], v142 offset:49152
	ds_read_b128 v[180:183], v142 offset:50176
	ds_read_b128 v[184:187], v142 offset:51200
	ds_read_b128 v[188:191], v142 offset:52224
	ds_read_b128 v[192:195], v142 offset:53248
	ds_read_b128 v[208:211], v142 offset:54272
	ds_read_b128 v[212:215], v142 offset:55296
	ds_read_b128 v[216:219], v142 offset:56320
	global_load_lds_dwordx4 v[222:223], off
	s_add_i32 m0, s40, 0x2000
	s_add_u32 s38, s38, 0x80080
	v_lshl_add_u64 v[222:223], v[224:225], 0, s[12:13]
	s_addc_u32 s39, s39, 0
	s_add_i32 s40, s64, s49
	global_load_lds_dwordx4 v[222:223], off
	s_mov_b32 m0, s40
	v_lshl_add_u64 v[222:223], s[38:39], 0, v[0:1]
	global_load_lds_dwordx4 v[222:223], off
	s_add_i32 m0, s40, 0x2000
	v_lshl_add_u64 v[222:223], s[38:39], 0, v[132:133]
	global_load_lds_dwordx4 v[222:223], off
	s_mov_b32 m0, s54
	v_lshl_add_u64 v[222:223], v[226:227], 0, s[12:13]
	global_load_lds_dwordx4 v[222:223], off
	s_mov_b32 m0, s55
	v_lshl_add_u64 v[222:223], v[228:229], 0, s[12:13]
	global_load_lds_dwordx4 v[222:223], off
	s_waitcnt vmcnt(8)
	s_waitcnt lgkmcnt(0)
	s_barrier
	v_mfma_f32_16x16x32_f16 v[64:67], v[144:147], v[176:179], v[64:67]
	v_mfma_f32_16x16x32_f16 v[60:63], v[152:155], v[176:179], v[60:63]
	v_mfma_f32_16x16x32_f16 v[48:51], v[144:147], v[184:187], v[48:51]
	v_mfma_f32_16x16x32_f16 v[44:47], v[152:155], v[184:187], v[44:47]
	v_mfma_f32_16x16x32_f16 v[32:35], v[144:147], v[192:195], v[32:35]
	v_mfma_f32_16x16x32_f16 v[28:31], v[152:155], v[192:195], v[28:31]
	v_mfma_f32_16x16x32_f16 v[16:19], v[144:147], v[212:215], v[16:19]
	v_mfma_f32_16x16x32_f16 v[12:15], v[152:155], v[212:215], v[12:15]
	v_mfma_f32_16x16x32_f16 v[64:67], v[148:151], v[180:183], v[64:67]
	v_mfma_f32_16x16x32_f16 v[60:63], v[156:159], v[180:183], v[60:63]
	v_mfma_f32_16x16x32_f16 v[48:51], v[148:151], v[188:191], v[48:51]
	v_mfma_f32_16x16x32_f16 v[44:47], v[156:159], v[188:191], v[44:47]
	v_mfma_f32_16x16x32_f16 v[32:35], v[148:151], v[208:211], v[32:35]
	v_mfma_f32_16x16x32_f16 v[28:31], v[156:159], v[208:211], v[28:31]
	v_mfma_f32_16x16x32_f16 v[16:19], v[148:151], v[216:219], v[16:19]
	v_mfma_f32_16x16x32_f16 v[12:15], v[156:159], v[216:219], v[12:15]
	v_mfma_f32_16x16x32_f16 v[56:59], v[160:163], v[176:179], v[56:59]
	v_mfma_f32_16x16x32_f16 v[52:55], v[168:171], v[176:179], v[52:55]
	v_mfma_f32_16x16x32_f16 v[40:43], v[160:163], v[184:187], v[40:43]
	v_mfma_f32_16x16x32_f16 v[36:39], v[168:171], v[184:187], v[36:39]
	v_mfma_f32_16x16x32_f16 v[24:27], v[160:163], v[192:195], v[24:27]
	v_mfma_f32_16x16x32_f16 v[20:23], v[168:171], v[192:195], v[20:23]
	v_mfma_f32_16x16x32_f16 v[8:11], v[160:163], v[212:215], v[8:11]
	v_mfma_f32_16x16x32_f16 v[4:7], v[168:171], v[212:215], v[4:7]
	v_mfma_f32_16x16x32_f16 v[56:59], v[164:167], v[180:183], v[56:59]
	v_mfma_f32_16x16x32_f16 v[52:55], v[172:175], v[180:183], v[52:55]
	v_mfma_f32_16x16x32_f16 v[40:43], v[164:167], v[188:191], v[40:43]
	v_mfma_f32_16x16x32_f16 v[36:39], v[172:175], v[188:191], v[36:39]
	v_mfma_f32_16x16x32_f16 v[24:27], v[164:167], v[208:211], v[24:27]
	v_mfma_f32_16x16x32_f16 v[20:23], v[172:175], v[208:211], v[20:23]
	v_mfma_f32_16x16x32_f16 v[8:11], v[164:167], v[216:219], v[8:11]
	v_mfma_f32_16x16x32_f16 v[4:7], v[172:175], v[216:219], v[4:7]
	s_barrier
	s_add_i32 s62, s62, 2
	s_add_u32 s36, s36, 0x100
	s_addc_u32 s37, s37, 0
	s_cmp_gt_u32 s62, 29
	s_cbranch_scc0 .LBB0_653
	s_and_b64 vcc, exec, s[22:23]
	s_cbranch_vccz .LBB0_656
	s_barrier

; #define PG8_STAGE(bufoff, gbase, voff) do { _Pragma("unroll") for (int _i = 0; _i < 2; ++_i) \
;         __builtin_amdgcn_global_load_lds((const unsigned*)((const char*)(gbase) + (voff)[_i]), (LAS unsigned*)(lds + (bufoff) + ldsw + _i * 8192), 16, 0, 0); } while (0)
; #define PG8_LDA(dst, b, h) do { _Pragma("unroll") for (int m = 0; m < 4; ++m) _Pragma("unroll") for (int k = 0; k < 2; ++k) dst[m][k] = *(const LAS bf16x8*)(lds + PG8_SA(b, h) + aoff + m * 2048 + k * 1024); } while (0)
; #define PG8_LDB(dst, b, h) do { _Pragma("unroll") for (int n = 0; n < 2; ++n) _Pragma("unroll") for (int k = 0; k < 2; ++k) dst[n][k] = *(const LAS bf16x8*)(lds + PG8_SB(b, h) + boff + n * 2048 + k * 1024); } while (0)
; #define PG8_WAIT_V(n) asm volatile("s_waitcnt vmcnt(" #n ")" ::: "memory")
; #define PG8_WAIT_L(n) asm volatile("s_waitcnt lgkmcnt(" #n ")" ::: "memory")
; #define PG8_BAR __builtin_amdgcn_s_barrier()
; #define PG8_SCHED __builtin_amdgcn_sched_barrier(0)
; template <class Epi, class Sched, bool FUSED = false, bool APERM = false>
; __device__ __forceinline__ void gemm_phase(int wid_s, LAS unsigned char* lds, const Gemm g, const Sched& S, const Epi& E) {
;     ...
;         for (int t = 0; t < nt; t += 2) {
;             const bool last = (t == nt - 2);
;             const char* a1 = cA + (size_t)(t + 1) * kstep;
;             const char* a2 = last ? nA : cA + (size_t)(t + 2) * kstep; const char* b2 = last ? nB : cB + (size_t)(t + 2) * kstep;
;             const char* a3 = a2 + kstep; const char* b3 = b2 + kstep;
;             if (last && has_next) S.a_ready(nxt);
;             PG8_LDB(B0, 0, 0); PG8_LDB(B1, 0, 1); PG8_SCHED; PG8_LDA(At, 0, 0); PG8_STAGE(PG8_SA(1, 1), a1 + hstep, voffA);
;             PG8_WAIT_V(8); PG8_WAIT_L(0); PG8_BAR; PG8_MMA(0, 0, At, B0); PG8_MMA(0, 1, At, B1); PG8_BAR; PG8_SCHED;
;             PG8_LDA(At, 0, 1); PG8_STAGE(PG8_SB(0, 0), b2, voffB); PG8_STAGE(PG8_SB(0, 1), b2 + hstep, voffB); PG8_STAGE(PG8_SA(0, 0), a2, voffA);
;             PG8_WAIT_V(8); PG8_WAIT_L(0); PG8_BAR; PG8_MMA(1, 0, At, B0); PG8_MMA(1, 1, At, B1); PG8_BAR; PG8_SCHED;
.LBB0_754:
	s_add_u32 s36, s6, 0x100
	s_addc_u32 s37, s7, 0
	s_add_i32 s45, 0, 0x10000
	s_cmp_eq_u32 s44, 28
	s_cselect_b32 s41, s3, s37
	s_cselect_b32 s40, s5, s36
	s_cselect_b32 s39, s27, s43
	s_cselect_b32 s38, s29, s42
	s_add_i32 s63, 0, 0x14000
	v_add_u32_e32 v80, s45, v244
	v_add_u32_e32 v96, s63, v244
	ds_read_b128 v[68:71], v80
	ds_read_b128 v[72:75], v80 offset:1024
	ds_read_b128 v[76:79], v80 offset:2048
	ds_read_b128 v[80:83], v80 offset:3072
	ds_read_b128 v[84:87], v96
	ds_read_b128 v[88:91], v96 offset:1024
	ds_read_b128 v[92:95], v96 offset:2048
	ds_read_b128 v[96:99], v96 offset:3072
	v_lshl_add_u64 v[200:201], s[6:7], 0, v[216:217]
	s_add_i32 m0, s52, 0xc000
	ds_read_b128 v[164:167], v245
	ds_read_b128 v[168:171], v245 offset:1024
	ds_read_b128 v[172:175], v245 offset:2048
	ds_read_b128 v[176:179], v245 offset:3072
	ds_read_b128 v[180:183], v245 offset:4096
	ds_read_b128 v[184:187], v245 offset:5120
	ds_read_b128 v[188:191], v245 offset:6144
	ds_read_b128 v[192:195], v245 offset:7168
	global_load_lds_dwordx4 v[200:201], off
	s_add_i32 m0, s52, 0xe000
	v_lshl_add_u64 v[200:201], s[6:7], 0, v[214:215]
	global_load_lds_dwordx4 v[200:201], off
	s_waitcnt vmcnt(8)
	s_waitcnt lgkmcnt(0)
	s_barrier
	v_mfma_f32_16x16x32_f16 v[160:163], v[68:71], v[164:167], v[160:163]
	v_mfma_f32_16x16x32_f16 v[64:67], v[76:79], v[164:167], v[64:67]
	v_mfma_f32_16x16x32_f16 v[148:151], v[68:71], v[172:175], v[148:151]
	v_mfma_f32_16x16x32_f16 v[48:51], v[76:79], v[172:175], v[48:51]
	v_mfma_f32_16x16x32_f16 v[132:135], v[68:71], v[180:183], v[132:135]
	v_mfma_f32_16x16x32_f16 v[36:39], v[76:79], v[180:183], v[36:39]
	v_mfma_f32_16x16x32_f16 v[144:147], v[68:71], v[188:191], v[144:147]
	v_mfma_f32_16x16x32_f16 v[44:47], v[76:79], v[188:191], v[44:47]
	v_mfma_f32_16x16x32_f16 v[160:163], v[72:75], v[168:171], v[160:163]
	v_mfma_f32_16x16x32_f16 v[64:67], v[80:83], v[168:171], v[64:67]
	v_mfma_f32_16x16x32_f16 v[148:151], v[72:75], v[176:179], v[148:151]
	v_mfma_f32_16x16x32_f16 v[48:51], v[80:83], v[176:179], v[48:51]
	v_mfma_f32_16x16x32_f16 v[132:135], v[72:75], v[184:187], v[132:135]
	v_mfma_f32_16x16x32_f16 v[36:39], v[80:83], v[184:187], v[36:39]
	v_mfma_f32_16x16x32_f16 v[144:147], v[72:75], v[192:195], v[144:147]
	v_mfma_f32_16x16x32_f16 v[44:47], v[80:83], v[192:195], v[44:47]
	v_mfma_f32_16x16x32_f16 v[156:159], v[84:87], v[164:167], v[156:159]
	v_mfma_f32_16x16x32_f16 v[60:63], v[92:95], v[164:167], v[60:63]
	v_mfma_f32_16x16x32_f16 v[152:155], v[84:87], v[172:175], v[152:155]
	v_mfma_f32_16x16x32_f16 v[56:59], v[92:95], v[172:175], v[56:59]
	v_mfma_f32_16x16x32_f16 v[140:143], v[84:87], v[180:183], v[140:143]
	v_mfma_f32_16x16x32_f16 v[40:43], v[92:95], v[180:183], v[40:43]
	v_mfma_f32_16x16x32_f16 v[136:139], v[84:87], v[188:191], v[136:139]
	v_mfma_f32_16x16x32_f16 v[52:55], v[92:95], v[188:191], v[52:55]
	v_mfma_f32_16x16x32_f16 v[156:159], v[88:91], v[168:171], v[156:159]
	v_mfma_f32_16x16x32_f16 v[60:63], v[96:99], v[168:171], v[60:63]
	v_mfma_f32_16x16x32_f16 v[152:155], v[88:91], v[176:179], v[152:155]
	v_mfma_f32_16x16x32_f16 v[56:59], v[96:99], v[176:179], v[56:59]
	v_mfma_f32_16x16x32_f16 v[140:143], v[88:91], v[184:187], v[140:143]
	v_mfma_f32_16x16x32_f16 v[40:43], v[96:99], v[184:187], v[40:43]
	v_mfma_f32_16x16x32_f16 v[136:139], v[88:91], v[192:195], v[136:139]
	v_mfma_f32_16x16x32_f16 v[52:55], v[96:99], v[192:195], v[52:55]
	s_barrier
	s_add_i32 s6, s45, s51
	v_lshl_add_u64 v[200:201], s[38:39], 0, v[208:209]
	s_mov_b32 m0, s6
	ds_read_b128 v[164:167], v245 offset:16384
	ds_read_b128 v[168:171], v245 offset:17408
	ds_read_b128 v[172:175], v245 offset:18432
	ds_read_b128 v[176:179], v245 offset:19456
	ds_read_b128 v[180:183], v245 offset:20480
	ds_read_b128 v[184:187], v245 offset:21504
	ds_read_b128 v[188:191], v245 offset:22528
	ds_read_b128 v[192:195], v245 offset:23552
	global_load_lds_dwordx4 v[200:201], off
	s_add_i32 m0, s6, 0x2000
	s_add_u32 s6, s38, 0x80000
	v_lshl_add_u64 v[234:235], s[38:39], 0, v[212:213]
	s_addc_u32 s7, s39, 0
	s_add_i32 s45, s63, s51
	global_load_lds_dwordx4 v[234:235], off
	v_lshl_add_u64 v[218:219], s[6:7], 0, v[208:209]
	s_mov_b32 m0, s45
	v_lshl_add_u64 v[236:237], s[40:41], 0, v[0:1]
	global_load_lds_dwordx4 v[218:219], off
	v_lshl_add_u64 v[218:219], s[6:7], 0, v[212:213]
	s_add_i32 m0, s45, 0x2000
	v_lshl_add_u64 v[238:239], s[40:41], 0, v[210:211]
	global_load_lds_dwordx4 v[218:219], off
	s_mov_b32 m0, s52
	s_nop 0
	global_load_lds_dwordx4 v[236:237], off
	s_mov_b32 m0, s53
	s_nop 0
	global_load_lds_dwordx4 v[238:239], off
	s_waitcnt vmcnt(8)
	s_waitcnt lgkmcnt(0)
	s_barrier
; #define PG8_STAGE(bufoff, gbase, voff) do { _Pragma("unroll") for (int _i = 0; _i < 2; ++_i) \
;         __builtin_amdgcn_global_load_lds((const unsigned*)((const char*)(gbase) + (voff)[_i]), (LAS unsigned*)(lds + (bufoff) + ldsw + _i * 8192), 16, 0, 0); } while (0)
; #define PG8_LDA(dst, b, h) do { _Pragma("unroll") for (int m = 0; m < 4; ++m) _Pragma("unroll") for (int k = 0; k < 2; ++k) dst[m][k] = *(const LAS bf16x8*)(lds + PG8_SA(b, h) + aoff + m * 2048 + k * 1024); } while (0)
; #define PG8_LDB(dst, b, h) do { _Pragma("unroll") for (int n = 0; n < 2; ++n) _Pragma("unroll") for (int k = 0; k < 2; ++k) dst[n][k] = *(const LAS bf16x8*)(lds + PG8_SB(b, h) + boff + n * 2048 + k * 1024); } while (0)
; #define PG8_WAIT_V(n) asm volatile("s_waitcnt vmcnt(" #n ")" ::: "memory")
; #define PG8_WAIT_L(n) asm volatile("s_waitcnt lgkmcnt(" #n ")" ::: "memory")
; #define PG8_BAR __builtin_amdgcn_s_barrier()
; #define PG8_SCHED __builtin_amdgcn_sched_barrier(0)
; template <class Epi, class Sched, bool FUSED = false, bool APERM = false>
; __device__ __forceinline__ void gemm_phase(int wid_s, LAS unsigned char* lds, const Gemm g, const Sched& S, const Epi& E) {
;     ...
;             PG8_WAIT_V(8); PG8_WAIT_L(0); PG8_BAR; PG8_MMA(1, 0, At, B0); PG8_MMA(1, 1, At, B1); PG8_BAR; PG8_SCHED;
;             PG8_LDB(B0, 1, 0); PG8_LDB(B1, 1, 1); PG8_SCHED; PG8_LDA(At, 1, 0); PG8_STAGE(PG8_SA(0, 1), a2 + hstep, voffA);
;             PG8_WAIT_V(8); PG8_WAIT_L(0); PG8_BAR; PG8_MMA(0, 0, At, B0); PG8_MMA(0, 1, At, B1); PG8_BAR; PG8_SCHED;
	v_mfma_f32_16x16x32_f16 v[128:131], v[68:71], v[164:167], v[128:131]
	v_mfma_f32_16x16x32_f16 v[32:35], v[76:79], v[164:167], v[32:35]
	v_mfma_f32_16x16x32_f16 v[120:123], v[68:71], v[172:175], v[120:123]
	v_mfma_f32_16x16x32_f16 v[24:27], v[76:79], v[172:175], v[24:27]
	v_mfma_f32_16x16x32_f16 v[100:103], v[68:71], v[180:183], v[100:103]
	v_mfma_f32_16x16x32_f16 v[8:11], v[76:79], v[180:183], v[8:11]
	v_mfma_f32_16x16x32_f16 v[112:115], v[68:71], v[188:191], v[112:115]
	v_mfma_f32_16x16x32_f16 v[4:7], v[76:79], v[188:191], v[4:7]
	v_mfma_f32_16x16x32_f16 v[128:131], v[72:75], v[168:171], v[128:131]
	v_mfma_f32_16x16x32_f16 v[32:35], v[80:83], v[168:171], v[32:35]
	v_mfma_f32_16x16x32_f16 v[120:123], v[72:75], v[176:179], v[120:123]
	v_mfma_f32_16x16x32_f16 v[24:27], v[80:83], v[176:179], v[24:27]
	v_mfma_f32_16x16x32_f16 v[100:103], v[72:75], v[184:187], v[100:103]
	v_mfma_f32_16x16x32_f16 v[8:11], v[80:83], v[184:187], v[8:11]
	v_mfma_f32_16x16x32_f16 v[112:115], v[72:75], v[192:195], v[112:115]
	v_mfma_f32_16x16x32_f16 v[4:7], v[80:83], v[192:195], v[4:7]
	v_mfma_f32_16x16x32_f16 v[28:31], v[92:95], v[164:167], v[28:31]
	v_mfma_f32_16x16x32_f16 v[20:23], v[92:95], v[172:175], v[20:23]
	v_mfma_f32_16x16x32_f16 v[16:19], v[92:95], v[180:183], v[16:19]
	v_mfma_f32_16x16x32_f16 v[12:15], v[92:95], v[188:191], v[12:15]
	v_mfma_f32_16x16x32_f16 v[68:71], v[84:87], v[164:167], v[124:127]
	v_mfma_f32_16x16x32_f16 v[28:31], v[96:99], v[168:171], v[28:31]
	v_mfma_f32_16x16x32_f16 v[72:75], v[84:87], v[172:175], v[116:119]
	v_mfma_f32_16x16x32_f16 v[20:23], v[96:99], v[176:179], v[20:23]
	v_mfma_f32_16x16x32_f16 v[76:79], v[84:87], v[180:183], v[108:111]
	v_mfma_f32_16x16x32_f16 v[16:19], v[96:99], v[184:187], v[16:19]
	v_mfma_f32_16x16x32_f16 v[80:83], v[84:87], v[188:191], v[104:107]
	v_mfma_f32_16x16x32_f16 v[12:15], v[96:99], v[192:195], v[12:15]
	v_mfma_f32_16x16x32_f16 v[68:71], v[88:91], v[168:171], v[68:71]
	v_mfma_f32_16x16x32_f16 v[72:75], v[88:91], v[176:179], v[72:75]
	v_mfma_f32_16x16x32_f16 v[76:79], v[88:91], v[184:187], v[76:79]
	v_mfma_f32_16x16x32_f16 v[80:83], v[88:91], v[192:195], v[80:83]
	s_barrier
	s_add_i32 s45, 0, 0x18000
	s_add_i32 s63, 0, 0x1c000
	v_add_u32_e32 v96, s45, v244
	v_add_u32_e32 v104, s63, v244
	ds_read_b128 v[84:87], v96
	ds_read_b128 v[88:91], v96 offset:1024
	ds_read_b128 v[92:95], v96 offset:2048
	ds_read_b128 v[96:99], v96 offset:3072
	ds_read_b128 v[164:167], v104
	ds_read_b128 v[168:171], v104 offset:1024
	ds_read_b128 v[172:175], v104 offset:2048
	ds_read_b128 v[176:179], v104 offset:3072
	s_add_u32 s6, s40, 0x80000
	s_addc_u32 s7, s41, 0
	s_mov_b32 m0, s54
	v_lshl_add_u64 v[218:219], s[6:7], 0, v[0:1]
	ds_read_b128 v[104:107], v245 offset:32768
	ds_read_b128 v[108:111], v245 offset:33792
	ds_read_b128 v[116:119], v245 offset:34816
	ds_read_b128 v[124:127], v245 offset:35840
	ds_read_b128 v[180:183], v245 offset:36864
	ds_read_b128 v[184:187], v245 offset:37888
	ds_read_b128 v[188:191], v245 offset:38912
	ds_read_b128 v[192:195], v245 offset:39936
	global_load_lds_dwordx4 v[218:219], off
	s_mov_b32 m0, s55
	v_lshl_add_u64 v[218:219], s[6:7], 0, v[210:211]
	global_load_lds_dwordx4 v[218:219], off
	s_waitcnt vmcnt(8)
	s_waitcnt lgkmcnt(0)
	s_barrier
	v_mfma_f32_16x16x32_f16 v[160:163], v[84:87], v[104:107], v[160:163]
	v_mfma_f32_16x16x32_f16 v[64:67], v[92:95], v[104:107], v[64:67]
	v_mfma_f32_16x16x32_f16 v[148:151], v[84:87], v[116:119], v[148:151]
	v_mfma_f32_16x16x32_f16 v[48:51], v[92:95], v[116:119], v[48:51]
	v_mfma_f32_16x16x32_f16 v[132:135], v[84:87], v[180:183], v[132:135]
	v_mfma_f32_16x16x32_f16 v[36:39], v[92:95], v[180:183], v[36:39]
	v_mfma_f32_16x16x32_f16 v[144:147], v[84:87], v[188:191], v[144:147]
	v_mfma_f32_16x16x32_f16 v[44:47], v[92:95], v[188:191], v[44:47]
	v_mfma_f32_16x16x32_f16 v[160:163], v[88:91], v[108:111], v[160:163]
	v_mfma_f32_16x16x32_f16 v[64:67], v[96:99], v[108:111], v[64:67]
	v_mfma_f32_16x16x32_f16 v[148:151], v[88:91], v[124:127], v[148:151]
	v_mfma_f32_16x16x32_f16 v[48:51], v[96:99], v[124:127], v[48:51]
	v_mfma_f32_16x16x32_f16 v[132:135], v[88:91], v[184:187], v[132:135]
	v_mfma_f32_16x16x32_f16 v[36:39], v[96:99], v[184:187], v[36:39]
	v_mfma_f32_16x16x32_f16 v[144:147], v[88:91], v[192:195], v[144:147]
	v_mfma_f32_16x16x32_f16 v[44:47], v[96:99], v[192:195], v[44:47]
	v_mfma_f32_16x16x32_f16 v[156:159], v[164:167], v[104:107], v[156:159]
	v_mfma_f32_16x16x32_f16 v[60:63], v[172:175], v[104:107], v[60:63]
	v_mfma_f32_16x16x32_f16 v[152:155], v[164:167], v[116:119], v[152:155]
	v_mfma_f32_16x16x32_f16 v[56:59], v[172:175], v[116:119], v[56:59]
	v_mfma_f32_16x16x32_f16 v[140:143], v[164:167], v[180:183], v[140:143]
	v_mfma_f32_16x16x32_f16 v[40:43], v[172:175], v[180:183], v[40:43]
	v_mfma_f32_16x16x32_f16 v[136:139], v[164:167], v[188:191], v[136:139]
	v_mfma_f32_16x16x32_f16 v[52:55], v[172:175], v[188:191], v[52:55]
	v_mfma_f32_16x16x32_f16 v[156:159], v[168:171], v[108:111], v[156:159]
	v_mfma_f32_16x16x32_f16 v[60:63], v[176:179], v[108:111], v[60:63]
	v_mfma_f32_16x16x32_f16 v[152:155], v[168:171], v[124:127], v[152:155]
	v_mfma_f32_16x16x32_f16 v[56:59], v[176:179], v[124:127], v[56:59]
	v_mfma_f32_16x16x32_f16 v[140:143], v[168:171], v[184:187], v[140:143]
	v_mfma_f32_16x16x32_f16 v[40:43], v[176:179], v[184:187], v[40:43]
	v_mfma_f32_16x16x32_f16 v[136:139], v[168:171], v[192:195], v[136:139]
	v_mfma_f32_16x16x32_f16 v[52:55], v[176:179], v[192:195], v[52:55]
	s_barrier
; #define PG8_STAGE(bufoff, gbase, voff) do { _Pragma("unroll") for (int _i = 0; _i < 2; ++_i) \
;         __builtin_amdgcn_global_load_lds((const unsigned*)((const char*)(gbase) + (voff)[_i]), (LAS unsigned*)(lds + (bufoff) + ldsw + _i * 8192), 16, 0, 0); } while (0)
; #define PG8_LDA(dst, b, h) do { _Pragma("unroll") for (int m = 0; m < 4; ++m) _Pragma("unroll") for (int k = 0; k < 2; ++k) dst[m][k] = *(const LAS bf16x8*)(lds + PG8_SA(b, h) + aoff + m * 2048 + k * 1024); } while (0)
; #define PG8_WAIT_V(n) asm volatile("s_waitcnt vmcnt(" #n ")" ::: "memory")
; #define PG8_WAIT_L(n) asm volatile("s_waitcnt lgkmcnt(" #n ")" ::: "memory")
; #define PG8_BAR __builtin_amdgcn_s_barrier()
; #define PG8_SCHED __builtin_amdgcn_sched_barrier(0)
; template <class Epi, class Sched, bool FUSED = false, bool APERM = false>
; __device__ __forceinline__ void gemm_phase(int wid_s, LAS unsigned char* lds, const Gemm g, const Sched& S, const Epi& E) {
;     ...
;             PG8_WAIT_V(8); PG8_WAIT_L(0); PG8_BAR; PG8_MMA(0, 0, At, B0); PG8_MMA(0, 1, At, B1); PG8_BAR; PG8_SCHED;
;             PG8_LDA(At, 1, 1); PG8_STAGE(PG8_SB(1, 0), b3, voffB); PG8_STAGE(PG8_SB(1, 1), b3 + hstep, voffB); PG8_STAGE(PG8_SA(1, 0), a3, voffA);
;             PG8_WAIT_V(8); PG8_WAIT_L(0); PG8_BAR; PG8_MMA(1, 0, At, B0); PG8_MMA(1, 1, At, B1); PG8_BAR; PG8_SCHED;
;         }
;         if (wr == 0) PG8_BAR;
	s_add_i32 s6, s45, s51
	v_lshl_add_u64 v[104:105], v[200:201], 0, s[12:13]
	s_mov_b32 m0, s6
	ds_read_b128 v[180:183], v245 offset:49152
	ds_read_b128 v[184:187], v245 offset:50176
	ds_read_b128 v[188:191], v245 offset:51200
	ds_read_b128 v[192:195], v245 offset:52224
	ds_read_b128 v[218:221], v245 offset:53248
	ds_read_b128 v[222:225], v245 offset:54272
	ds_read_b128 v[226:229], v245 offset:55296
	ds_read_b128 v[230:233], v245 offset:56320
	global_load_lds_dwordx4 v[104:105], off
	s_add_i32 m0, s6, 0x2000
	s_add_u32 s6, s38, 0x80080
	v_lshl_add_u64 v[104:105], v[234:235], 0, s[12:13]
	s_addc_u32 s7, s39, 0
	s_add_i32 s38, s63, s51
	global_load_lds_dwordx4 v[104:105], off
	s_mov_b32 m0, s38
	v_lshl_add_u64 v[104:105], s[6:7], 0, v[208:209]
	global_load_lds_dwordx4 v[104:105], off
	s_add_i32 m0, s38, 0x2000
	v_lshl_add_u64 v[104:105], s[6:7], 0, v[212:213]
	global_load_lds_dwordx4 v[104:105], off
	s_mov_b32 m0, s59
	v_lshl_add_u64 v[104:105], v[236:237], 0, s[12:13]
	global_load_lds_dwordx4 v[104:105], off
	s_mov_b32 m0, s60
	v_lshl_add_u64 v[104:105], v[238:239], 0, s[12:13]
	global_load_lds_dwordx4 v[104:105], off
	s_waitcnt vmcnt(8)
	s_waitcnt lgkmcnt(0)
	s_barrier
	v_mfma_f32_16x16x32_f16 v[104:107], v[84:87], v[180:183], v[128:131]
	v_mfma_f32_16x16x32_f16 v[128:131], v[88:91], v[184:187], v[104:107]
	v_mfma_f32_16x16x32_f16 v[104:107], v[84:87], v[188:191], v[120:123]
	v_mfma_f32_16x16x32_f16 v[32:35], v[92:95], v[180:183], v[32:35]
	v_mfma_f32_16x16x32_f16 v[120:123], v[88:91], v[192:195], v[104:107]
	v_mfma_f32_16x16x32_f16 v[24:27], v[92:95], v[188:191], v[24:27]
	v_mfma_f32_16x16x32_f16 v[100:103], v[84:87], v[218:221], v[100:103]
	v_mfma_f32_16x16x32_f16 v[8:11], v[92:95], v[218:221], v[8:11]
	v_mfma_f32_16x16x32_f16 v[104:107], v[84:87], v[226:229], v[112:115]
	v_mfma_f32_16x16x32_f16 v[4:7], v[92:95], v[226:229], v[4:7]
	v_mfma_f32_16x16x32_f16 v[32:35], v[96:99], v[184:187], v[32:35]
	v_mfma_f32_16x16x32_f16 v[24:27], v[96:99], v[192:195], v[24:27]
	v_mfma_f32_16x16x32_f16 v[100:103], v[88:91], v[222:225], v[100:103]
	v_mfma_f32_16x16x32_f16 v[8:11], v[96:99], v[222:225], v[8:11]
	v_mfma_f32_16x16x32_f16 v[112:115], v[88:91], v[230:233], v[104:107]
	v_mfma_f32_16x16x32_f16 v[4:7], v[96:99], v[230:233], v[4:7]
	v_mfma_f32_16x16x32_f16 v[68:71], v[164:167], v[180:183], v[68:71]
	v_mfma_f32_16x16x32_f16 v[124:127], v[168:171], v[184:187], v[68:71]
	v_mfma_f32_16x16x32_f16 v[68:71], v[164:167], v[188:191], v[72:75]
	v_mfma_f32_16x16x32_f16 v[116:119], v[168:171], v[192:195], v[68:71]
	v_mfma_f32_16x16x32_f16 v[68:71], v[164:167], v[218:221], v[76:79]
	v_mfma_f32_16x16x32_f16 v[28:31], v[172:175], v[180:183], v[28:31]
	v_mfma_f32_16x16x32_f16 v[20:23], v[172:175], v[188:191], v[20:23]
	v_mfma_f32_16x16x32_f16 v[108:111], v[168:171], v[222:225], v[68:71]
	v_mfma_f32_16x16x32_f16 v[16:19], v[172:175], v[218:221], v[16:19]
	v_mfma_f32_16x16x32_f16 v[68:71], v[164:167], v[226:229], v[80:83]
	v_mfma_f32_16x16x32_f16 v[12:15], v[172:175], v[226:229], v[12:15]
	v_mfma_f32_16x16x32_f16 v[28:31], v[176:179], v[184:187], v[28:31]
	v_mfma_f32_16x16x32_f16 v[20:23], v[176:179], v[192:195], v[20:23]
	v_mfma_f32_16x16x32_f16 v[16:19], v[176:179], v[222:225], v[16:19]
	v_mfma_f32_16x16x32_f16 v[104:107], v[168:171], v[230:233], v[68:71]
	v_mfma_f32_16x16x32_f16 v[12:15], v[176:179], v[230:233], v[12:15]
	s_barrier
	s_add_i32 s44, s44, 2
	s_add_u32 s42, s42, 0x100
	s_addc_u32 s43, s43, 0
	s_cmp_gt_u32 s44, 29
	s_mov_b64 s[6:7], s[36:37]
	s_cbranch_scc0 .LBB0_754
	s_and_b64 vcc, exec, s[24:25]
	s_cbranch_vccz .LBB0_757
	s_barrier

; #define PG8_STAGE(bufoff, gbase, voff) do { _Pragma("unroll") for (int _i = 0; _i < 2; ++_i) \
;         __builtin_amdgcn_global_load_lds((const unsigned*)((const char*)(gbase) + (voff)[_i]), (LAS unsigned*)(lds + (bufoff) + ldsw + _i * 8192), 16, 0, 0); } while (0)
; #define PG8_LDA(dst, b, h) do { _Pragma("unroll") for (int m = 0; m < 4; ++m) _Pragma("unroll") for (int k = 0; k < 2; ++k) dst[m][k] = *(const LAS bf16x8*)(lds + PG8_SA(b, h) + aoff + m * 2048 + k * 1024); } while (0)
; #define PG8_LDB(dst, b, h) do { _Pragma("unroll") for (int n = 0; n < 2; ++n) _Pragma("unroll") for (int k = 0; k < 2; ++k) dst[n][k] = *(const LAS bf16x8*)(lds + PG8_SB(b, h) + boff + n * 2048 + k * 1024); } while (0)
; #define PG8_WAIT_V(n) asm volatile("s_waitcnt vmcnt(" #n ")" ::: "memory")
; #define PG8_WAIT_L(n) asm volatile("s_waitcnt lgkmcnt(" #n ")" ::: "memory")
; #define PG8_BAR __builtin_amdgcn_s_barrier()
; #define PG8_SCHED __builtin_amdgcn_sched_barrier(0)
; template <class Epi, class Sched, bool FUSED = false, bool APERM = false>
; __device__ __forceinline__ void gemm_phase(int wid_s, LAS unsigned char* lds, const Gemm g, const Sched& S, const Epi& E) {
;     ...
;         for (int t = 0; t < nt; t += 2) {
;             const bool last = (t == nt - 2);
;             const char* a1 = cA + (size_t)(t + 1) * kstep;
;             const char* a2 = last ? nA : cA + (size_t)(t + 2) * kstep; const char* b2 = last ? nB : cB + (size_t)(t + 2) * kstep;
;             const char* a3 = a2 + kstep; const char* b3 = b2 + kstep;
;             if (last && has_next) S.a_ready(nxt);
;             PG8_LDB(B0, 0, 0); PG8_LDB(B1, 0, 1); PG8_SCHED; PG8_LDA(At, 0, 0); PG8_STAGE(PG8_SA(1, 1), a1 + hstep, voffA);
;             PG8_WAIT_V(8); PG8_WAIT_L(0); PG8_BAR; PG8_MMA(0, 0, At, B0); PG8_MMA(0, 1, At, B1); PG8_BAR; PG8_SCHED;
;             PG8_LDA(At, 0, 1); PG8_STAGE(PG8_SB(0, 0), b2, voffB); PG8_STAGE(PG8_SB(0, 1), b2 + hstep, voffB); PG8_STAGE(PG8_SA(0, 0), a2, voffA);
;             PG8_WAIT_V(8); PG8_WAIT_L(0); PG8_BAR; PG8_MMA(1, 0, At, B0); PG8_MMA(1, 1, At, B1); PG8_BAR; PG8_SCHED;
.LBB0_929:
	s_add_u32 s36, s28, s34
	s_addc_u32 s37, s29, s35
	s_add_u32 s36, s36, 0x100
	s_addc_u32 s37, s37, 0
	s_add_u32 s63, s60, s34
	s_addc_u32 s64, s61, s35
	s_add_i32 s65, 0, 0x10000
	s_cmpk_eq_i32 s34, 0x2a00
	s_cselect_b32 s39, s5, s37
	s_cselect_b32 s38, s4, s36
	v_add_u32_e32 v143, s65, v3
	s_cselect_b32 s37, s31, s64
	s_cselect_b32 s36, s30, s63
	s_add_i32 s63, 0, 0x14000
	ds_read_b128 v[144:147], v143
	ds_read_b128 v[148:151], v143 offset:1024
	ds_read_b128 v[152:155], v143 offset:2048
	ds_read_b128 v[156:159], v143 offset:3072
	v_add_u32_e32 v143, s63, v3
	ds_read_b128 v[160:163], v143
	ds_read_b128 v[164:167], v143 offset:1024
	ds_read_b128 v[168:171], v143 offset:2048
	ds_read_b128 v[172:175], v143 offset:3072
	v_lshl_add_u64 v[200:201], v[140:141], 0, s[34:35]
	s_add_i32 m0, s49, 0xc000
	ds_read_b128 v[176:179], v142
	ds_read_b128 v[180:183], v142 offset:1024
	ds_read_b128 v[184:187], v142 offset:2048
	ds_read_b128 v[188:191], v142 offset:3072
	ds_read_b128 v[192:195], v142 offset:4096
	ds_read_b128 v[208:211], v142 offset:5120
	ds_read_b128 v[212:215], v142 offset:6144
	ds_read_b128 v[216:219], v142 offset:7168
	global_load_lds_dwordx4 v[200:201], off
	s_add_i32 m0, s49, 0xe000
	v_lshl_add_u64 v[200:201], v[138:139], 0, s[34:35]
	global_load_lds_dwordx4 v[200:201], off
	s_waitcnt vmcnt(8)
	s_waitcnt lgkmcnt(0)
	s_barrier
	v_mfma_f32_16x16x32_f16 v[128:131], v[144:147], v[176:179], v[128:131]
	v_mfma_f32_16x16x32_f16 v[124:127], v[152:155], v[176:179], v[124:127]
	v_mfma_f32_16x16x32_f16 v[112:115], v[144:147], v[184:187], v[112:115]
	v_mfma_f32_16x16x32_f16 v[108:111], v[152:155], v[184:187], v[108:111]
	v_mfma_f32_16x16x32_f16 v[96:99], v[144:147], v[192:195], v[96:99]
	v_mfma_f32_16x16x32_f16 v[92:95], v[152:155], v[192:195], v[92:95]
	v_mfma_f32_16x16x32_f16 v[80:83], v[144:147], v[212:215], v[80:83]
	v_mfma_f32_16x16x32_f16 v[76:79], v[152:155], v[212:215], v[76:79]
	v_mfma_f32_16x16x32_f16 v[128:131], v[148:151], v[180:183], v[128:131]
	v_mfma_f32_16x16x32_f16 v[124:127], v[156:159], v[180:183], v[124:127]
	v_mfma_f32_16x16x32_f16 v[112:115], v[148:151], v[188:191], v[112:115]
	v_mfma_f32_16x16x32_f16 v[108:111], v[156:159], v[188:191], v[108:111]
	v_mfma_f32_16x16x32_f16 v[96:99], v[148:151], v[208:211], v[96:99]
	v_mfma_f32_16x16x32_f16 v[92:95], v[156:159], v[208:211], v[92:95]
	v_mfma_f32_16x16x32_f16 v[80:83], v[148:151], v[216:219], v[80:83]
	v_mfma_f32_16x16x32_f16 v[76:79], v[156:159], v[216:219], v[76:79]
	v_mfma_f32_16x16x32_f16 v[120:123], v[160:163], v[176:179], v[120:123]
	v_mfma_f32_16x16x32_f16 v[116:119], v[168:171], v[176:179], v[116:119]
	v_mfma_f32_16x16x32_f16 v[104:107], v[160:163], v[184:187], v[104:107]
	v_mfma_f32_16x16x32_f16 v[100:103], v[168:171], v[184:187], v[100:103]
	v_mfma_f32_16x16x32_f16 v[88:91], v[160:163], v[192:195], v[88:91]
	v_mfma_f32_16x16x32_f16 v[84:87], v[168:171], v[192:195], v[84:87]
	v_mfma_f32_16x16x32_f16 v[72:75], v[160:163], v[212:215], v[72:75]
	v_mfma_f32_16x16x32_f16 v[68:71], v[168:171], v[212:215], v[68:71]
	v_mfma_f32_16x16x32_f16 v[120:123], v[164:167], v[180:183], v[120:123]
	v_mfma_f32_16x16x32_f16 v[116:119], v[172:175], v[180:183], v[116:119]
	v_mfma_f32_16x16x32_f16 v[104:107], v[164:167], v[188:191], v[104:107]
	v_mfma_f32_16x16x32_f16 v[100:103], v[172:175], v[188:191], v[100:103]
	v_mfma_f32_16x16x32_f16 v[88:91], v[164:167], v[208:211], v[88:91]
	v_mfma_f32_16x16x32_f16 v[84:87], v[172:175], v[208:211], v[84:87]
	v_mfma_f32_16x16x32_f16 v[72:75], v[164:167], v[216:219], v[72:75]
	v_mfma_f32_16x16x32_f16 v[68:71], v[172:175], v[216:219], v[68:71]
	s_barrier
	s_add_i32 s64, s65, s48
	v_lshl_add_u64 v[200:201], s[36:37], 0, v[0:1]
	s_mov_b32 m0, s64
	ds_read_b128 v[176:179], v142 offset:16384
	ds_read_b128 v[180:183], v142 offset:17408
	ds_read_b128 v[184:187], v142 offset:18432
	ds_read_b128 v[188:191], v142 offset:19456
	ds_read_b128 v[192:195], v142 offset:20480
	ds_read_b128 v[208:211], v142 offset:21504
	ds_read_b128 v[212:215], v142 offset:22528
	ds_read_b128 v[216:219], v142 offset:23552
	global_load_lds_dwordx4 v[200:201], off
	s_add_i32 m0, s64, 0x2000
	s_add_u32 s64, s36, 0x158000
	v_lshl_add_u64 v[222:223], s[36:37], 0, v[132:133]
	s_addc_u32 s65, s37, 0
	s_add_i32 s63, s63, s48
	global_load_lds_dwordx4 v[222:223], off
	v_lshl_add_u64 v[224:225], s[64:65], 0, v[0:1]
	s_mov_b32 m0, s63
	v_lshl_add_u64 v[226:227], s[38:39], 0, v[132:133]
	global_load_lds_dwordx4 v[224:225], off
	s_add_i32 m0, s63, 0x2000
	v_lshl_add_u64 v[224:225], s[64:65], 0, v[132:133]
	global_load_lds_dwordx4 v[224:225], off
	s_mov_b32 m0, s49
	v_lshl_add_u64 v[224:225], s[38:39], 0, v[0:1]
	global_load_lds_dwordx4 v[224:225], off
	s_mov_b32 m0, s50
	s_nop 0
	global_load_lds_dwordx4 v[226:227], off
	s_waitcnt vmcnt(8)
	s_waitcnt lgkmcnt(0)
	s_barrier
; #define PG8_STAGE(bufoff, gbase, voff) do { _Pragma("unroll") for (int _i = 0; _i < 2; ++_i) \
;         __builtin_amdgcn_global_load_lds((const unsigned*)((const char*)(gbase) + (voff)[_i]), (LAS unsigned*)(lds + (bufoff) + ldsw + _i * 8192), 16, 0, 0); } while (0)
; #define PG8_LDA(dst, b, h) do { _Pragma("unroll") for (int m = 0; m < 4; ++m) _Pragma("unroll") for (int k = 0; k < 2; ++k) dst[m][k] = *(const LAS bf16x8*)(lds + PG8_SA(b, h) + aoff + m * 2048 + k * 1024); } while (0)
; #define PG8_LDB(dst, b, h) do { _Pragma("unroll") for (int n = 0; n < 2; ++n) _Pragma("unroll") for (int k = 0; k < 2; ++k) dst[n][k] = *(const LAS bf16x8*)(lds + PG8_SB(b, h) + boff + n * 2048 + k * 1024); } while (0)
; #define PG8_WAIT_V(n) asm volatile("s_waitcnt vmcnt(" #n ")" ::: "memory")
; #define PG8_WAIT_L(n) asm volatile("s_waitcnt lgkmcnt(" #n ")" ::: "memory")
; #define PG8_BAR __builtin_amdgcn_s_barrier()
; #define PG8_SCHED __builtin_amdgcn_sched_barrier(0)
; template <class Epi, class Sched, bool FUSED = false, bool APERM = false>
; __device__ __forceinline__ void gemm_phase(int wid_s, LAS unsigned char* lds, const Gemm g, const Sched& S, const Epi& E) {
;     ...
;             PG8_WAIT_V(8); PG8_WAIT_L(0); PG8_BAR; PG8_MMA(1, 0, At, B0); PG8_MMA(1, 1, At, B1); PG8_BAR; PG8_SCHED;
;             PG8_LDB(B0, 1, 0); PG8_LDB(B1, 1, 1); PG8_SCHED; PG8_LDA(At, 1, 0); PG8_STAGE(PG8_SA(0, 1), a2 + hstep, voffA);
;             PG8_WAIT_V(8); PG8_WAIT_L(0); PG8_BAR; PG8_MMA(0, 0, At, B0); PG8_MMA(0, 1, At, B1); PG8_BAR; PG8_SCHED;
	v_mfma_f32_16x16x32_f16 v[64:67], v[144:147], v[176:179], v[64:67]
	v_mfma_f32_16x16x32_f16 v[60:63], v[152:155], v[176:179], v[60:63]
	v_mfma_f32_16x16x32_f16 v[48:51], v[144:147], v[184:187], v[48:51]
	v_mfma_f32_16x16x32_f16 v[44:47], v[152:155], v[184:187], v[44:47]
	v_mfma_f32_16x16x32_f16 v[32:35], v[144:147], v[192:195], v[32:35]
	v_mfma_f32_16x16x32_f16 v[28:31], v[152:155], v[192:195], v[28:31]
	v_mfma_f32_16x16x32_f16 v[16:19], v[144:147], v[212:215], v[16:19]
	v_mfma_f32_16x16x32_f16 v[12:15], v[152:155], v[212:215], v[12:15]
	v_mfma_f32_16x16x32_f16 v[64:67], v[148:151], v[180:183], v[64:67]
	v_mfma_f32_16x16x32_f16 v[60:63], v[156:159], v[180:183], v[60:63]
	v_mfma_f32_16x16x32_f16 v[48:51], v[148:151], v[188:191], v[48:51]
	v_mfma_f32_16x16x32_f16 v[44:47], v[156:159], v[188:191], v[44:47]
	v_mfma_f32_16x16x32_f16 v[32:35], v[148:151], v[208:211], v[32:35]
	v_mfma_f32_16x16x32_f16 v[28:31], v[156:159], v[208:211], v[28:31]
	v_mfma_f32_16x16x32_f16 v[16:19], v[148:151], v[216:219], v[16:19]
	v_mfma_f32_16x16x32_f16 v[12:15], v[156:159], v[216:219], v[12:15]
	v_mfma_f32_16x16x32_f16 v[56:59], v[160:163], v[176:179], v[56:59]
	v_mfma_f32_16x16x32_f16 v[52:55], v[168:171], v[176:179], v[52:55]
	v_mfma_f32_16x16x32_f16 v[40:43], v[160:163], v[184:187], v[40:43]
	v_mfma_f32_16x16x32_f16 v[36:39], v[168:171], v[184:187], v[36:39]
	v_mfma_f32_16x16x32_f16 v[24:27], v[160:163], v[192:195], v[24:27]
	v_mfma_f32_16x16x32_f16 v[20:23], v[168:171], v[192:195], v[20:23]
	v_mfma_f32_16x16x32_f16 v[8:11], v[160:163], v[212:215], v[8:11]
	v_mfma_f32_16x16x32_f16 v[4:7], v[168:171], v[212:215], v[4:7]
	v_mfma_f32_16x16x32_f16 v[56:59], v[164:167], v[180:183], v[56:59]
	v_mfma_f32_16x16x32_f16 v[52:55], v[172:175], v[180:183], v[52:55]
	v_mfma_f32_16x16x32_f16 v[40:43], v[164:167], v[188:191], v[40:43]
	v_mfma_f32_16x16x32_f16 v[36:39], v[172:175], v[188:191], v[36:39]
	v_mfma_f32_16x16x32_f16 v[24:27], v[164:167], v[208:211], v[24:27]
	v_mfma_f32_16x16x32_f16 v[20:23], v[172:175], v[208:211], v[20:23]
	v_mfma_f32_16x16x32_f16 v[8:11], v[164:167], v[216:219], v[8:11]
	v_mfma_f32_16x16x32_f16 v[4:7], v[172:175], v[216:219], v[4:7]
	s_barrier
	s_add_i32 s63, 0, 0x18000
	v_add_u32_e32 v143, s63, v3
	s_add_i32 s64, 0, 0x1c000
	ds_read_b128 v[144:147], v143
	ds_read_b128 v[148:151], v143 offset:1024
	ds_read_b128 v[152:155], v143 offset:2048
	ds_read_b128 v[156:159], v143 offset:3072
	v_add_u32_e32 v143, s64, v3
	ds_read_b128 v[160:163], v143
	ds_read_b128 v[164:167], v143 offset:1024
	ds_read_b128 v[168:171], v143 offset:2048
	ds_read_b128 v[172:175], v143 offset:3072
	s_add_u32 s38, s38, 0x158000
	s_addc_u32 s39, s39, 0
	s_mov_b32 m0, s51
	v_lshl_add_u64 v[228:229], s[38:39], 0, v[0:1]
	ds_read_b128 v[176:179], v142 offset:32768
	ds_read_b128 v[180:183], v142 offset:33792
	ds_read_b128 v[184:187], v142 offset:34816
	ds_read_b128 v[188:191], v142 offset:35840
	ds_read_b128 v[192:195], v142 offset:36864
	ds_read_b128 v[208:211], v142 offset:37888
	ds_read_b128 v[212:215], v142 offset:38912
	ds_read_b128 v[216:219], v142 offset:39936
	global_load_lds_dwordx4 v[228:229], off
	s_mov_b32 m0, s52
	v_lshl_add_u64 v[228:229], s[38:39], 0, v[132:133]
	global_load_lds_dwordx4 v[228:229], off
	s_waitcnt vmcnt(8)
	s_waitcnt lgkmcnt(0)
	s_barrier
	v_mfma_f32_16x16x32_f16 v[128:131], v[144:147], v[176:179], v[128:131]
	v_mfma_f32_16x16x32_f16 v[124:127], v[152:155], v[176:179], v[124:127]
	v_mfma_f32_16x16x32_f16 v[112:115], v[144:147], v[184:187], v[112:115]
	v_mfma_f32_16x16x32_f16 v[108:111], v[152:155], v[184:187], v[108:111]
	v_mfma_f32_16x16x32_f16 v[96:99], v[144:147], v[192:195], v[96:99]
	v_mfma_f32_16x16x32_f16 v[92:95], v[152:155], v[192:195], v[92:95]
	v_mfma_f32_16x16x32_f16 v[80:83], v[144:147], v[212:215], v[80:83]
	v_mfma_f32_16x16x32_f16 v[76:79], v[152:155], v[212:215], v[76:79]
	v_mfma_f32_16x16x32_f16 v[128:131], v[148:151], v[180:183], v[128:131]
	v_mfma_f32_16x16x32_f16 v[124:127], v[156:159], v[180:183], v[124:127]
	v_mfma_f32_16x16x32_f16 v[112:115], v[148:151], v[188:191], v[112:115]
	v_mfma_f32_16x16x32_f16 v[108:111], v[156:159], v[188:191], v[108:111]
	v_mfma_f32_16x16x32_f16 v[96:99], v[148:151], v[208:211], v[96:99]
	v_mfma_f32_16x16x32_f16 v[92:95], v[156:159], v[208:211], v[92:95]
	v_mfma_f32_16x16x32_f16 v[80:83], v[148:151], v[216:219], v[80:83]
	v_mfma_f32_16x16x32_f16 v[76:79], v[156:159], v[216:219], v[76:79]
	v_mfma_f32_16x16x32_f16 v[120:123], v[160:163], v[176:179], v[120:123]
	v_mfma_f32_16x16x32_f16 v[116:119], v[168:171], v[176:179], v[116:119]
	v_mfma_f32_16x16x32_f16 v[104:107], v[160:163], v[184:187], v[104:107]
	v_mfma_f32_16x16x32_f16 v[100:103], v[168:171], v[184:187], v[100:103]
	v_mfma_f32_16x16x32_f16 v[88:91], v[160:163], v[192:195], v[88:91]
	v_mfma_f32_16x16x32_f16 v[84:87], v[168:171], v[192:195], v[84:87]
	v_mfma_f32_16x16x32_f16 v[72:75], v[160:163], v[212:215], v[72:75]
	v_mfma_f32_16x16x32_f16 v[68:71], v[168:171], v[212:215], v[68:71]
	v_mfma_f32_16x16x32_f16 v[120:123], v[164:167], v[180:183], v[120:123]
	v_mfma_f32_16x16x32_f16 v[116:119], v[172:175], v[180:183], v[116:119]
	v_mfma_f32_16x16x32_f16 v[104:107], v[164:167], v[188:191], v[104:107]
	v_mfma_f32_16x16x32_f16 v[100:103], v[172:175], v[188:191], v[100:103]
	v_mfma_f32_16x16x32_f16 v[88:91], v[164:167], v[208:211], v[88:91]
	v_mfma_f32_16x16x32_f16 v[84:87], v[172:175], v[208:211], v[84:87]
	v_mfma_f32_16x16x32_f16 v[72:75], v[164:167], v[216:219], v[72:75]
	v_mfma_f32_16x16x32_f16 v[68:71], v[172:175], v[216:219], v[68:71]
	s_barrier
; #define PG8_STAGE(bufoff, gbase, voff) do { _Pragma("unroll") for (int _i = 0; _i < 2; ++_i) \
;         __builtin_amdgcn_global_load_lds((const unsigned*)((const char*)(gbase) + (voff)[_i]), (LAS unsigned*)(lds + (bufoff) + ldsw + _i * 8192), 16, 0, 0); } while (0)
; #define PG8_LDA(dst, b, h) do { _Pragma("unroll") for (int m = 0; m < 4; ++m) _Pragma("unroll") for (int k = 0; k < 2; ++k) dst[m][k] = *(const LAS bf16x8*)(lds + PG8_SA(b, h) + aoff + m * 2048 + k * 1024); } while (0)
; #define PG8_WAIT_V(n) asm volatile("s_waitcnt vmcnt(" #n ")" ::: "memory")
; #define PG8_WAIT_L(n) asm volatile("s_waitcnt lgkmcnt(" #n ")" ::: "memory")
; #define PG8_BAR __builtin_amdgcn_s_barrier()
; #define PG8_SCHED __builtin_amdgcn_sched_barrier(0)
; template <class Epi, class Sched, bool FUSED = false, bool APERM = false>
; __device__ __forceinline__ void gemm_phase(int wid_s, LAS unsigned char* lds, const Gemm g, const Sched& S, const Epi& E) {
;     ...
;             PG8_WAIT_V(8); PG8_WAIT_L(0); PG8_BAR; PG8_MMA(0, 0, At, B0); PG8_MMA(0, 1, At, B1); PG8_BAR; PG8_SCHED;
;             PG8_LDA(At, 1, 1); PG8_STAGE(PG8_SB(1, 0), b3, voffB); PG8_STAGE(PG8_SB(1, 1), b3 + hstep, voffB); PG8_STAGE(PG8_SA(1, 0), a3, voffA);
;             PG8_WAIT_V(8); PG8_WAIT_L(0); PG8_BAR; PG8_MMA(1, 0, At, B0); PG8_MMA(1, 1, At, B1); PG8_BAR; PG8_SCHED;
;         }
;         if (wr == 0) PG8_BAR;
	s_add_i32 s38, s63, s48
	v_lshl_add_u64 v[200:201], v[200:201], 0, s[12:13]
	s_mov_b32 m0, s38
	ds_read_b128 v[176:179], v142 offset:49152
	ds_read_b128 v[180:183], v142 offset:50176
	ds_read_b128 v[184:187], v142 offset:51200
	ds_read_b128 v[188:191], v142 offset:52224
	ds_read_b128 v[192:195], v142 offset:53248
	ds_read_b128 v[208:211], v142 offset:54272
	ds_read_b128 v[212:215], v142 offset:55296
	ds_read_b128 v[216:219], v142 offset:56320
	global_load_lds_dwordx4 v[200:201], off
	s_add_i32 m0, s38, 0x2000
	s_add_u32 s36, s36, 0x158080
	v_lshl_add_u64 v[200:201], v[222:223], 0, s[12:13]
	s_addc_u32 s37, s37, 0
	s_add_i32 s38, s64, s48
	global_load_lds_dwordx4 v[200:201], off
	s_mov_b32 m0, s38
	v_lshl_add_u64 v[200:201], s[36:37], 0, v[0:1]
	global_load_lds_dwordx4 v[200:201], off
	s_add_i32 m0, s38, 0x2000
	v_lshl_add_u64 v[200:201], s[36:37], 0, v[132:133]
	global_load_lds_dwordx4 v[200:201], off
	s_mov_b32 m0, s54
	v_lshl_add_u64 v[200:201], v[224:225], 0, s[12:13]
	global_load_lds_dwordx4 v[200:201], off
	s_mov_b32 m0, s55
	v_lshl_add_u64 v[200:201], v[226:227], 0, s[12:13]
	global_load_lds_dwordx4 v[200:201], off
	s_waitcnt vmcnt(8)
	s_waitcnt lgkmcnt(0)
	s_barrier
	v_mfma_f32_16x16x32_f16 v[64:67], v[144:147], v[176:179], v[64:67]
	v_mfma_f32_16x16x32_f16 v[60:63], v[152:155], v[176:179], v[60:63]
	v_mfma_f32_16x16x32_f16 v[48:51], v[144:147], v[184:187], v[48:51]
	v_mfma_f32_16x16x32_f16 v[44:47], v[152:155], v[184:187], v[44:47]
	v_mfma_f32_16x16x32_f16 v[32:35], v[144:147], v[192:195], v[32:35]
	v_mfma_f32_16x16x32_f16 v[28:31], v[152:155], v[192:195], v[28:31]
	v_mfma_f32_16x16x32_f16 v[16:19], v[144:147], v[212:215], v[16:19]
	v_mfma_f32_16x16x32_f16 v[12:15], v[152:155], v[212:215], v[12:15]
	v_mfma_f32_16x16x32_f16 v[64:67], v[148:151], v[180:183], v[64:67]
	v_mfma_f32_16x16x32_f16 v[60:63], v[156:159], v[180:183], v[60:63]
	v_mfma_f32_16x16x32_f16 v[48:51], v[148:151], v[188:191], v[48:51]
	v_mfma_f32_16x16x32_f16 v[44:47], v[156:159], v[188:191], v[44:47]
	v_mfma_f32_16x16x32_f16 v[32:35], v[148:151], v[208:211], v[32:35]
	v_mfma_f32_16x16x32_f16 v[28:31], v[156:159], v[208:211], v[28:31]
	v_mfma_f32_16x16x32_f16 v[16:19], v[148:151], v[216:219], v[16:19]
	v_mfma_f32_16x16x32_f16 v[12:15], v[156:159], v[216:219], v[12:15]
	v_mfma_f32_16x16x32_f16 v[56:59], v[160:163], v[176:179], v[56:59]
	v_mfma_f32_16x16x32_f16 v[52:55], v[168:171], v[176:179], v[52:55]
	v_mfma_f32_16x16x32_f16 v[40:43], v[160:163], v[184:187], v[40:43]
	v_mfma_f32_16x16x32_f16 v[36:39], v[168:171], v[184:187], v[36:39]
	v_mfma_f32_16x16x32_f16 v[24:27], v[160:163], v[192:195], v[24:27]
	v_mfma_f32_16x16x32_f16 v[20:23], v[168:171], v[192:195], v[20:23]
	v_mfma_f32_16x16x32_f16 v[8:11], v[160:163], v[212:215], v[8:11]
	v_mfma_f32_16x16x32_f16 v[4:7], v[168:171], v[212:215], v[4:7]
	v_mfma_f32_16x16x32_f16 v[56:59], v[164:167], v[180:183], v[56:59]
	v_mfma_f32_16x16x32_f16 v[52:55], v[172:175], v[180:183], v[52:55]
	v_mfma_f32_16x16x32_f16 v[40:43], v[164:167], v[188:191], v[40:43]
	v_mfma_f32_16x16x32_f16 v[36:39], v[172:175], v[188:191], v[36:39]
	v_mfma_f32_16x16x32_f16 v[24:27], v[164:167], v[208:211], v[24:27]
	v_mfma_f32_16x16x32_f16 v[20:23], v[172:175], v[208:211], v[20:23]
	v_mfma_f32_16x16x32_f16 v[8:11], v[164:167], v[216:219], v[8:11]
	v_mfma_f32_16x16x32_f16 v[4:7], v[172:175], v[216:219], v[4:7]
	s_barrier
	s_add_i32 s62, s62, 2
	s_add_u32 s34, s34, 0x100
	s_addc_u32 s35, s35, 0
	s_cmpk_gt_u32 s62, 0x53
	s_cbranch_scc0 .LBB0_929
	s_and_b64 vcc, exec, s[26:27]
	s_cbranch_vccz .LBB0_932
	s_barrier
